# mixer attention part rewritten by hand: per wave 4 sub-tiles, Q norm/gains applied once, bias values loaded once, batched LDS reads, branch-free masks, v_rsq/v_rcp; plus parameter warm-up loads
# speedup vs baseline: 1.0192x; 1.0132x over previous
; __device__ __forceinline__ void mixer_phase256(const Args& A, int l, int vc, const bf16* Z, bf16* MIX, ss_t* ssa, ss_t* ssb, unsigned char* lds, int tid, int wid, int lane) {
;     ...
;     const int gx = vc & 7, gj = vc >> 3;
;     const int n = 8 * gx + (gj >> 2), kvh = gj & 3, h = gj & 15, cb = 8 * gx + 4 * (gj >> 4);
;     const int fr = lane & 15, fq = lane >> 4;
;     const bool isK = tid < 256; const int arow = tid & 255; const int atok = (n - 1) * 128 + arow;
;     u32x4 aw[8], sw[8];
;     { const bf16* ap = Z + (size_t)(atok < 0 ? 0 : atok) * INW + (isK ? KCOL : VCOL) + kvh * 64;
; #pragma unroll
;       for (int c = 0; c < 8; ++c) aw[c] = *(const u32x4*)(ap + 8 * c); }
;     const int srow = tid & 127, sj = tid >> 7;
;     { const bf16* sp = Z + (size_t)((cb + sj) * 128 + srow) * INW + 1024 + h * 64;
; #pragma unroll
;       for (int c = 0; c < 8; ++c) sw[c] = *(const u32x4*)(sp + 8 * c); }
.LBB0_505:
	s_and_b64 vcc, exec, s[2:3]
	s_cbranch_vccz .LBB0_803
	v_lshlrev_b32_e32 v253, 2, v174
	v_lshlrev_b32_e32 v251, 2, v113
	s_lshl_b32 s2, s78, 8
	v_readlane_b32 s100, v250, 30
	v_readlane_b32 s101, v250, 31
	v_readlane_b32 s3, v248, 3
	s_nop 0
	s_add_u32 s100, s100, s2
	s_addc_u32 s101, s101, 0
	s_nop 0
	global_load_dword v254, v253, s[100:101]
	v_readlane_b32 s100, v250, 26
	v_readlane_b32 s101, v250, 27
	s_nop 0
	s_add_u32 s100, s100, s2
	s_addc_u32 s101, s101, 0
	s_nop 0
	global_load_dword v254, v253, s[100:101]
	s_lshl_b32 s2, s78, 4
	s_or_b32 s2, s2, s3
	s_lshl_b32 s2, s2, 8
	v_readlane_b32 s100, v250, 20
	v_readlane_b32 s101, v250, 21
	s_nop 0
	s_add_u32 s100, s100, s2
	s_addc_u32 s101, s101, 0
	s_nop 0
	global_load_dword v254, v253, s[100:101]
	v_readlane_b32 s100, v250, 14
	v_readlane_b32 s101, v250, 15
	s_nop 4
	global_load_dword v254, v251, s[100:101]
	v_readlane_b32 s100, v250, 32
	v_readlane_b32 s101, v250, 33
	s_nop 4
	global_load_dword v254, v253, s[100:101]
	v_and_b32_e32 v178, 0xff, v113
	v_readlane_b32 s2, v248, 2
	v_mov_b64_e32 v[0:1], s[82:83]
	v_mov_b32_e32 v5, v2
	v_add_u32_e32 v100, s2, v178
	v_max_i32_e32 v3, 0, v100
	v_mad_u64_u32 v[0:1], s[2:3], v3, s85, v[0:1]
	s_movk_i32 s2, 0x100
	s_nop 0
	v_cmp_gt_i32_e32 vcc, s2, v113
	v_readlane_b32 s2, v247, 25
	v_readlane_b32 s3, v247, 26
	v_cndmask_b32_e32 v4, v210, v211, vcc
	v_lshl_add_u64 v[0:1], v[0:1], 0, v[4:5]
	s_mov_b32 s4, s2
	s_mov_b32 s5, s77
	v_writelane_b32 v247, s2, 25
	v_lshl_add_u64 v[0:1], v[0:1], 0, s[4:5]
	v_ashrrev_i32_e32 v177, 7, v113
	v_writelane_b32 v247, s3, 26
	v_readlane_b32 s2, v248, 6
	global_load_dwordx4 v[76:79], v[0:1], off offset:48
	global_load_dwordx4 v[80:83], v[0:1], off offset:32
	global_load_dwordx4 v[84:87], v[0:1], off offset:16
	global_load_dwordx4 v[88:91], v[0:1], off
	global_load_dwordx4 v[92:95], v[0:1], off offset:112
	global_load_dwordx4 v[96:99], v[0:1], off offset:96
	global_load_dwordx4 v[68:71], v[0:1], off offset:80
	global_load_dwordx4 v[72:75], v[0:1], off offset:64
	v_add_u32_e32 v0, s2, v177
	v_readlane_b32 s2, v248, 4
	v_and_b32_e32 v3, 0x7f, v113
	v_readlane_b32 s3, v248, 5
	v_lshl_or_b32 v4, v0, 7, v3
	s_lshl_b32 s37, s78, 4
	v_mov_b64_e32 v[0:1], s[2:3]
	v_mad_i64_i32 v[0:1], s[2:3], v4, s85, v[0:1]
	global_load_dwordx4 v[44:47], v[0:1], off offset:2096
	global_load_dwordx4 v[48:51], v[0:1], off offset:2080
	global_load_dwordx4 v[52:55], v[0:1], off offset:2064
	global_load_dwordx4 v[56:59], v[0:1], off offset:2048
	global_load_dwordx4 v[60:63], v[0:1], off offset:2160
	global_load_dwordx4 v[64:67], v[0:1], off offset:2144
	global_load_dwordx4 v[4:7], v[0:1], off offset:2128
	global_load_dwordx4 v[8:11], v[0:1], off offset:2112
	v_readlane_b32 s4, v248, 3
	s_or_b32 s38, s37, s4
	v_and_b32_e32 v175, 15, v113
	s_ashr_i32 s36, s17, 7
	s_lshl_b32 s4, s38, 16
	v_lshl_or_b32 v114, s73, 4, v175
	s_add_u32 s4, s50, s4
	v_ashrrev_i32_e32 v115, 31, v114
	s_addc_u32 s5, s51, 0
	v_lshrrev_b32_e32 v176, 4, v174
	v_lshlrev_b64 v[0:1], 9, v[114:115]
	s_cmp_gt_i32 s36, -1
	s_movk_i32 s2, 0xff
	v_lshl_add_u64 v[0:1], s[4:5], 0, v[0:1]
	v_lshlrev_b32_e32 v12, 5, v176
	v_mov_b32_e32 v13, v2
	s_cselect_b64 s[8:9], -1, 0
	v_cmp_lt_i32_e64 s[2:3], s2, v113
	v_lshl_add_u64 v[0:1], v[0:1], 0, v[12:13]
	v_mov_b32_e32 v16, 0
	s_and_b64 vcc, exec, s[8:9]
	v_mov_b32_e32 v40, 0
	v_mov_b32_e32 v41, 0
	v_mov_b32_e32 v42, 0
	v_mov_b32_e32 v43, 0
	v_mov_b32_e32 v36, 0
	v_mov_b32_e32 v37, 0
	v_mov_b32_e32 v38, 0
	v_mov_b32_e32 v39, 0
	s_cbranch_vccz .LBB0_508
	global_load_dwordx4 v[40:43], v[0:1], off
	global_load_dwordx4 v[36:39], v[0:1], off offset:16

; __device__ __forceinline__ unsigned pkbf(float lo, float hi) { typedef float f2_t __attribute__((ext_vector_type(2))); typedef __bf16 b2_t __attribute__((ext_vector_type(2))); f2_t v = {lo, hi}; b2_t b = __builtin_convertvector(v, b2_t); return __builtin_bit_cast(unsigned, b); }
; __device__ __forceinline__ float bflo(unsigned w) { return __uint_as_float(w << 16); }
; __device__ __forceinline__ float bfhi(unsigned w) { return __uint_as_float(w & 0xffff0000u); }
; __device__ __forceinline__ void mixer_phase256(const Args& A, int l, int vc, const bf16* Z, bf16* MIX, ss_t* ssa, ss_t* ssb, unsigned char* lds, int tid, int wid, int lane) {
;     ...
;     { const float* gs = A.sgu_norm_g + (l * 16 + h) * 64; float ss = 0.f; bf16* vn = VN + sj * 64 * VN_STRIDE;
; #pragma unroll
;       for (int c = 0; c < 8; ++c)
; #pragma unroll
;           for (int e = 0; e < 4; ++e) { const float a = bflo(sw[c][e]), b = bfhi(sw[c][e]); ss += a * a + b * b; }
;       const float rstd = 1.0f / sqrtf(ss * (1.0f / 64.f) + EPS);
; #pragma unroll
;       for (int c = 0; c < 8; ++c) { const f32x4 g0 = *(const f32x4*)(gs + 8 * c), g1 = *(const f32x4*)(gs + 8 * c + 4); const float gg[8] = {g0.x, g0.y, g0.z, g0.w, g1.x, g1.y, g1.z, g1.w};
; #pragma unroll
;           for (int e = 0; e < 4; ++e) { const unsigned w = pkbf(bflo(sw[c][e]) * rstd * gg[2 * e], bfhi(sw[c][e]) * rstd * gg[2 * e + 1]);
;               vn[(8 * c + 2 * e) * VN_STRIDE + srow] = (bf16)(w & 0xffffu); vn[(8 * c + 2 * e + 1) * VN_STRIDE + srow] = (bf16)(w >> 16); } }
.LBB0_520:
	s_or_b64 exec, exec, s[12:13]
	v_and_b32_e32 v91, 0xffff0000, v65
	v_and_b32_e32 v90, 0xffff0000, v64
	s_lshl_b32 s76, s38, 6
	s_movk_i32 s2, 0x4400
	v_lshlrev_b32_e32 v89, 16, v65
	v_lshlrev_b32_e32 v88, 16, v64
	v_pk_mul_f32 v[0:1], v[90:91], v[90:91]
	v_and_b32_e32 v87, 0xffff0000, v67
	v_and_b32_e32 v86, 0xffff0000, v66
	v_mul_lo_u32 v77, v177, s2
	v_pk_fma_f32 v[104:105], v[88:89], v[88:89], v[0:1]
	v_lshlrev_b32_e32 v85, 16, v67
	v_lshlrev_b32_e32 v84, 16, v66
	v_pk_mul_f32 v[0:1], v[86:87], v[86:87]
	v_and_b32_e32 v83, 0xffff0000, v61
	v_and_b32_e32 v82, 0xffff0000, v60
	s_lshl_b64 s[2:3], s[76:77], 2
	v_pk_fma_f32 v[106:107], v[84:85], v[84:85], v[0:1]
	v_lshlrev_b32_e32 v81, 16, v61
	v_lshlrev_b32_e32 v80, 16, v60
	v_pk_mul_f32 v[0:1], v[82:83], v[82:83]
	v_and_b32_e32 v79, 0xffff0000, v63
	v_and_b32_e32 v78, 0xffff0000, v62
	s_add_u32 s12, s48, s2
	v_pk_fma_f32 v[108:109], v[80:81], v[80:81], v[0:1]
	v_lshlrev_b32_e32 v1, 16, v63
	v_lshlrev_b32_e32 v0, 16, v62
	v_pk_mul_f32 v[60:61], v[78:79], v[78:79]
	s_addc_u32 s13, s49, s3
	v_pk_fma_f32 v[110:111], v[0:1], v[0:1], v[60:61]
	global_load_dwordx4 v[60:63], v2, s[12:13] offset:48
	global_load_dwordx4 v[64:67], v2, s[12:13] offset:32
	global_load_dwordx4 v[68:71], v2, s[12:13] offset:16
	global_load_dwordx4 v[72:75], v2, s[12:13]
	v_lshlrev_b32_e32 v136, 16, v56
	v_and_b32_e32 v137, 0xffff0000, v56
	v_lshlrev_b32_e32 v138, 16, v57
	v_and_b32_e32 v139, 0xffff0000, v57
	v_pk_mul_f32 v[116:117], v[136:137], v[136:137]
	v_pk_mul_f32 v[118:119], v[138:139], v[138:139]
	v_lshlrev_b32_e32 v140, 16, v58
	v_and_b32_e32 v141, 0xffff0000, v58
	v_pk_mul_f32 v[120:121], v[140:141], v[140:141]
	v_lshlrev_b32_e32 v142, 16, v59
	v_and_b32_e32 v143, 0xffff0000, v59
	v_add_f32_e32 v118, v118, v119
	v_add_f32_e32 v116, v116, v117
	v_pk_mul_f32 v[122:123], v[142:143], v[142:143]
	v_lshlrev_b32_e32 v144, 16, v52
	v_and_b32_e32 v145, 0xffff0000, v52
	v_add_f32_e32 v116, v116, v118
	v_add_f32_e32 v117, v120, v121
	v_pk_mul_f32 v[124:125], v[144:145], v[144:145]
	v_lshlrev_b32_e32 v146, 16, v53
	v_and_b32_e32 v147, 0xffff0000, v53
	v_add_f32_e32 v115, v122, v123
	v_add_f32_e32 v116, v117, v116
	v_pk_mul_f32 v[126:127], v[146:147], v[146:147]
	v_lshlrev_b32_e32 v148, 16, v54
	v_and_b32_e32 v149, 0xffff0000, v54
	v_add_f32_e32 v115, v115, v116
	v_add_f32_e32 v116, v124, v125
	v_pk_mul_f32 v[128:129], v[148:149], v[148:149]
	v_lshlrev_b32_e32 v150, 16, v55
	v_and_b32_e32 v151, 0xffff0000, v55
	v_add_f32_e32 v115, v116, v115
	v_add_f32_e32 v116, v126, v127
	v_pk_mul_f32 v[130:131], v[150:151], v[150:151]
	v_lshlrev_b32_e32 v152, 16, v48
	v_and_b32_e32 v153, 0xffff0000, v48
	v_add_f32_e32 v115, v116, v115
	v_add_f32_e32 v116, v128, v129
	v_pk_mul_f32 v[132:133], v[152:153], v[152:153]
	v_lshlrev_b32_e32 v154, 16, v49
	v_and_b32_e32 v155, 0xffff0000, v49
	v_add_f32_e32 v115, v116, v115
	v_add_f32_e32 v116, v130, v131
	v_pk_mul_f32 v[134:135], v[154:155], v[154:155]
	v_lshlrev_b32_e32 v92, 16, v50
	v_and_b32_e32 v93, 0xffff0000, v50
	v_add_f32_e32 v115, v116, v115
	v_add_f32_e32 v116, v132, v133
	v_pk_mul_f32 v[156:157], v[92:93], v[92:93]
	v_lshlrev_b32_e32 v48, 16, v51
	v_and_b32_e32 v49, 0xffff0000, v51
	v_add_f32_e32 v115, v116, v115
	v_add_f32_e32 v116, v134, v135
	v_pk_mul_f32 v[158:159], v[48:49], v[48:49]
	v_lshlrev_b32_e32 v96, 16, v44
	v_and_b32_e32 v97, 0xffff0000, v44
	v_add_f32_e32 v115, v116, v115
	v_add_f32_e32 v116, v156, v157
	v_pk_mul_f32 v[172:173], v[96:97], v[96:97]
	v_lshlrev_b32_e32 v94, 16, v45
	v_and_b32_e32 v95, 0xffff0000, v45
	v_add_f32_e32 v115, v116, v115
	v_add_f32_e32 v116, v158, v159
	v_pk_mul_f32 v[178:179], v[94:95], v[94:95]
	v_lshlrev_b32_e32 v50, 16, v46
	v_and_b32_e32 v51, 0xffff0000, v46
	v_add_f32_e32 v115, v116, v115
	v_add_f32_e32 v116, v172, v173
	v_pk_mul_f32 v[180:181], v[50:51], v[50:51]
	v_lshlrev_b32_e32 v44, 16, v47
	v_and_b32_e32 v45, 0xffff0000, v47
	v_add_f32_e32 v115, v116, v115
	v_add_f32_e32 v116, v178, v179
	v_pk_mul_f32 v[182:183], v[44:45], v[44:45]
	v_lshlrev_b32_e32 v46, 16, v8
	v_and_b32_e32 v47, 0xffff0000, v8
	v_add_f32_e32 v115, v116, v115
	v_add_f32_e32 v116, v180, v181
	v_pk_mul_f32 v[184:185], v[46:47], v[46:47]
	v_lshlrev_b32_e32 v8, 16, v9
	v_and_b32_e32 v9, 0xffff0000, v9
	v_add_f32_e32 v115, v116, v115
	v_add_f32_e32 v116, v182, v183
	v_pk_mul_f32 v[186:187], v[8:9], v[8:9]
	v_lshlrev_b32_e32 v98, 16, v10
	v_and_b32_e32 v99, 0xffff0000, v10
	v_add_f32_e32 v115, v116, v115
	v_add_f32_e32 v116, v184, v185
	v_pk_mul_f32 v[188:189], v[98:99], v[98:99]
	v_lshlrev_b32_e32 v10, 16, v11
	v_and_b32_e32 v11, 0xffff0000, v11
	v_add_f32_e32 v115, v116, v115
	v_add_f32_e32 v116, v186, v187
	v_pk_mul_f32 v[190:191], v[10:11], v[10:11]
	v_lshlrev_b32_e32 v100, 16, v4
	v_and_b32_e32 v101, 0xffff0000, v4
	v_add_f32_e32 v115, v116, v115
	v_add_f32_e32 v116, v188, v189
	global_load_dwordx4 v[52:55], v2, s[12:13] offset:80
	global_load_dwordx4 v[56:59], v2, s[12:13] offset:64
	v_pk_mul_f32 v[192:193], v[100:101], v[100:101]
	v_lshlrev_b32_e32 v4, 16, v5
	v_and_b32_e32 v5, 0xffff0000, v5
	v_add_f32_e32 v115, v116, v115
	v_add_f32_e32 v116, v190, v191
	v_pk_mul_f32 v[194:195], v[4:5], v[4:5]
	v_lshlrev_b32_e32 v102, 16, v6
	v_and_b32_e32 v103, 0xffff0000, v6
	v_add_f32_e32 v115, v116, v115
	v_add_f32_e32 v116, v192, v193
	v_pk_mul_f32 v[196:197], v[102:103], v[102:103]
	v_lshlrev_b32_e32 v6, 16, v7
	v_and_b32_e32 v7, 0xffff0000, v7
	v_add_f32_e32 v115, v116, v115
	v_add_f32_e32 v116, v194, v195
	v_pk_mul_f32 v[198:199], v[6:7], v[6:7]
	v_add_f32_e32 v115, v116, v115
	v_add_f32_e32 v116, v196, v197
	v_add_f32_e32 v115, v116, v115
; __device__ __forceinline__ unsigned pkbf(float lo, float hi) { typedef float f2_t __attribute__((ext_vector_type(2))); typedef __bf16 b2_t __attribute__((ext_vector_type(2))); f2_t v = {lo, hi}; b2_t b = __builtin_convertvector(v, b2_t); return __builtin_bit_cast(unsigned, b); }
; __device__ __forceinline__ float bflo(unsigned w) { return __uint_as_float(w << 16); }
; __device__ __forceinline__ float bfhi(unsigned w) { return __uint_as_float(w & 0xffff0000u); }
; __device__ __forceinline__ void mixer_phase256(const Args& A, int l, int vc, const bf16* Z, bf16* MIX, ss_t* ssa, ss_t* ssb, unsigned char* lds, int tid, int wid, int lane) {
;     ...
;       const float rstd = 1.0f / sqrtf(ss * (1.0f / 64.f) + EPS);
; #pragma unroll
;       for (int c = 0; c < 8; ++c) { const f32x4 g0 = *(const f32x4*)(gs + 8 * c), g1 = *(const f32x4*)(gs + 8 * c + 4); const float gg[8] = {g0.x, g0.y, g0.z, g0.w, g1.x, g1.y, g1.z, g1.w};
; #pragma unroll
;           for (int e = 0; e < 4; ++e) { const unsigned w = pkbf(bflo(sw[c][e]) * rstd * gg[2 * e], bfhi(sw[c][e]) * rstd * gg[2 * e + 1]);
;               vn[(8 * c + 2 * e) * VN_STRIDE + srow] = (bf16)(w & 0xffffu); vn[(8 * c + 2 * e + 1) * VN_STRIDE + srow] = (bf16)(w >> 16); } }
	v_add_f32_e32 v116, v198, v199
	v_add_f32_e32 v115, v116, v115
	v_add_f32_e32 v104, v104, v115
	v_add_f32_e32 v104, v105, v104
	v_add_f32_e32 v104, v106, v104
	v_add_f32_e32 v104, v107, v104
	v_add_f32_e32 v104, v108, v104
	v_add_f32_e32 v104, v109, v104
	global_load_dwordx4 v[106:109], v2, s[12:13] offset:112
	global_load_dwordx4 v[116:119], v2, s[12:13] offset:96
	v_add_f32_e32 v104, v110, v104
	v_add_f32_e32 v104, v111, v104
	v_fmamk_f32 v104, v104, 0x3c800000, v205
	v_mul_f32_e32 v105, 0x4f800000, v104
	v_cmp_gt_f32_e32 vcc, s97, v104
	v_lshlrev_b32_e32 v3, 1, v3
	v_readlane_b32 s14, v247, 27
	v_cndmask_b32_e32 v104, v104, v105, vcc
	v_sqrt_f32_e32 v105, v104
	v_add3_u32 v3, s14, v77, v3
	global_load_dwordx4 v[120:123], v2, s[12:13] offset:176
	global_load_dwordx4 v[124:127], v2, s[12:13] offset:160
	global_load_dwordx4 v[128:131], v2, s[12:13] offset:144
	global_load_dwordx4 v[132:135], v2, s[12:13] offset:128
	v_lshlrev_b32_e32 v76, 3, v176
	v_add_u32_e32 v77, -1, v105
	v_fma_f32 v110, -v77, v105, v104
	v_cmp_ge_f32_e64 s[2:3], 0, v110
	v_add_u32_e32 v110, 1, v105
	s_nop 0
	v_cndmask_b32_e64 v77, v105, v77, s[2:3]
	v_fma_f32 v105, -v110, v105, v104
	v_cmp_lt_f32_e64 s[2:3], 0, v105
	s_nop 1
	v_cndmask_b32_e64 v77, v77, v110, s[2:3]
	v_mul_f32_e32 v105, 0x37800000, v77
	v_cndmask_b32_e32 v77, v77, v105, vcc
	v_cmp_class_f32_e32 vcc, v104, v206
	s_nop 1
	v_cndmask_b32_e32 v77, v77, v104, vcc
	v_div_scale_f32 v104, s[2:3], v77, v77, 1.0
	v_rcp_f32_e32 v105, v104
	s_and_b32 s2, s17, 64
	v_readlane_b32 s3, v248, 1
	s_or_b32 s2, s3, s2
	v_fma_f32 v110, -v104, v105, 1.0
	v_fmac_f32_e32 v105, v110, v105
	v_div_scale_f32 v110, vcc, 1.0, v77, 1.0
	v_mul_f32_e32 v111, v110, v105
	v_fma_f32 v115, -v104, v111, v110
	v_fmac_f32_e32 v111, v115, v105
	v_fma_f32 v104, -v104, v111, v110
	v_div_fmas_f32 v104, v104, v105, v111
	v_div_fixup_f32 v104, v104, v77, 1.0
	v_pk_mul_f32 v[110:111], v[104:105], v[136:137] op_sel_hi:[0,1]
	s_waitcnt vmcnt(8)
	v_pk_mul_f32 v[72:73], v[110:111], v[72:73]
	v_pk_mul_f32 v[48:49], v[104:105], v[48:49] op_sel_hi:[0,1]
	v_cvt_pk_bf16_f32 v72, v72, v73
	ds_write_b16 v3, v72
	ds_write_b16_d16_hi v3, v72 offset:272
	v_pk_mul_f32 v[72:73], v[104:105], v[138:139] op_sel_hi:[0,1]
	v_pk_mul_f32 v[72:73], v[72:73], v[74:75]
	s_waitcnt vmcnt(7)
	v_pk_mul_f32 v[48:49], v[48:49], v[54:55]
	v_cvt_pk_bf16_f32 v72, v72, v73
	ds_write_b16 v3, v72 offset:544
	ds_write_b16_d16_hi v3, v72 offset:816
	v_pk_mul_f32 v[72:73], v[104:105], v[140:141] op_sel_hi:[0,1]
	v_pk_mul_f32 v[68:69], v[72:73], v[68:69]
	v_cvt_pk_bf16_f32 v48, v48, v49
	v_cvt_pk_bf16_f32 v68, v68, v69
	ds_write_b16 v3, v68 offset:1088
	ds_write_b16_d16_hi v3, v68 offset:1360
	v_pk_mul_f32 v[68:69], v[104:105], v[142:143] op_sel_hi:[0,1]
	v_pk_mul_f32 v[68:69], v[68:69], v[70:71]
	v_pk_mul_f32 v[44:45], v[104:105], v[44:45] op_sel_hi:[0,1]
	v_cvt_pk_bf16_f32 v68, v68, v69
	ds_write_b16 v3, v68 offset:1632
	ds_write_b16_d16_hi v3, v68 offset:1904
	v_pk_mul_f32 v[68:69], v[104:105], v[144:145] op_sel_hi:[0,1]
	v_pk_mul_f32 v[64:65], v[68:69], v[64:65]
	v_pk_mul_f32 v[8:9], v[104:105], v[8:9] op_sel_hi:[0,1]
	v_cvt_pk_bf16_f32 v64, v64, v65
	ds_write_b16 v3, v64 offset:2176
	ds_write_b16_d16_hi v3, v64 offset:2448
	v_pk_mul_f32 v[64:65], v[104:105], v[146:147] op_sel_hi:[0,1]
	v_pk_mul_f32 v[64:65], v[64:65], v[66:67]
	v_pk_mul_f32 v[4:5], v[104:105], v[4:5] op_sel_hi:[0,1]
	v_cvt_pk_bf16_f32 v64, v64, v65
	ds_write_b16 v3, v64 offset:2720
	ds_write_b16_d16_hi v3, v64 offset:2992
	v_pk_mul_f32 v[64:65], v[104:105], v[148:149] op_sel_hi:[0,1]
	v_pk_mul_f32 v[60:61], v[64:65], v[60:61]
	v_mov_b32_e32 v77, v2
	v_cvt_pk_bf16_f32 v60, v60, v61
	ds_write_b16 v3, v60 offset:3264
	ds_write_b16_d16_hi v3, v60 offset:3536
	v_pk_mul_f32 v[60:61], v[104:105], v[150:151] op_sel_hi:[0,1]
	v_pk_mul_f32 v[60:61], v[60:61], v[62:63]
	s_waitcnt vmcnt(5)
	v_pk_mul_f32 v[44:45], v[44:45], v[108:109]
	v_cvt_pk_bf16_f32 v60, v60, v61
	ds_write_b16 v3, v60 offset:3808
	ds_write_b16_d16_hi v3, v60 offset:4080
	v_pk_mul_f32 v[60:61], v[104:105], v[152:153] op_sel_hi:[0,1]
	v_pk_mul_f32 v[56:57], v[60:61], v[56:57]
	v_cvt_pk_bf16_f32 v44, v44, v45
	v_cvt_pk_bf16_f32 v56, v56, v57
	ds_write_b16 v3, v56 offset:4352
	ds_write_b16_d16_hi v3, v56 offset:4624
	global_load_dwordx4 v[60:63], v2, s[12:13] offset:208
	global_load_dwordx4 v[64:67], v2, s[12:13] offset:192
	v_pk_mul_f32 v[56:57], v[104:105], v[154:155] op_sel_hi:[0,1]
	v_pk_mul_f32 v[56:57], v[56:57], v[58:59]
	s_waitcnt vmcnt(2)
; __device__ __forceinline__ unsigned pkbf(float lo, float hi) { typedef float f2_t __attribute__((ext_vector_type(2))); typedef __bf16 b2_t __attribute__((ext_vector_type(2))); f2_t v = {lo, hi}; b2_t b = __builtin_convertvector(v, b2_t); return __builtin_bit_cast(unsigned, b); }
; __device__ __forceinline__ float bflo(unsigned w) { return __uint_as_float(w << 16); }
; __device__ __forceinline__ float bfhi(unsigned w) { return __uint_as_float(w & 0xffff0000u); }
; __device__ __forceinline__ void mixer_phase256(const Args& A, int l, int vc, const bf16* Z, bf16* MIX, ss_t* ssa, ss_t* ssb, unsigned char* lds, int tid, int wid, int lane) {
;     ...
;       for (int c = 0; c < 8; ++c) { const f32x4 g0 = *(const f32x4*)(gs + 8 * c), g1 = *(const f32x4*)(gs + 8 * c + 4); const float gg[8] = {g0.x, g0.y, g0.z, g0.w, g1.x, g1.y, g1.z, g1.w};
; #pragma unroll
;           for (int e = 0; e < 4; ++e) { const unsigned w = pkbf(bflo(sw[c][e]) * rstd * gg[2 * e], bfhi(sw[c][e]) * rstd * gg[2 * e + 1]);
;               vn[(8 * c + 2 * e) * VN_STRIDE + srow] = (bf16)(w & 0xffffu); vn[(8 * c + 2 * e + 1) * VN_STRIDE + srow] = (bf16)(w >> 16); } }
	v_pk_mul_f32 v[8:9], v[8:9], v[134:135]
	v_cvt_pk_bf16_f32 v56, v56, v57
	ds_write_b16 v3, v56 offset:4896
	ds_write_b16_d16_hi v3, v56 offset:5168
	v_pk_mul_f32 v[56:57], v[104:105], v[92:93] op_sel_hi:[0,1]
	v_pk_mul_f32 v[52:53], v[56:57], v[52:53]
	v_cvt_pk_bf16_f32 v8, v8, v9
	v_cvt_pk_bf16_f32 v52, v52, v53
	ds_write_b16 v3, v52 offset:5440
	ds_write_b16_d16_hi v3, v52 offset:5712
	ds_write_b16 v3, v48 offset:5984
	ds_write_b16_d16_hi v3, v48 offset:6256
	v_pk_mul_f32 v[48:49], v[104:105], v[96:97] op_sel_hi:[0,1]
	v_pk_mul_f32 v[48:49], v[48:49], v[116:117]
	v_pk_mul_f32 v[4:5], v[4:5], v[126:127]
	v_cvt_pk_bf16_f32 v48, v48, v49
	ds_write_b16 v3, v48 offset:6528
	ds_write_b16_d16_hi v3, v48 offset:6800
	v_pk_mul_f32 v[48:49], v[104:105], v[94:95] op_sel_hi:[0,1]
	v_pk_mul_f32 v[48:49], v[48:49], v[118:119]
	v_cvt_pk_bf16_f32 v4, v4, v5
	v_cvt_pk_bf16_f32 v48, v48, v49
	ds_write_b16 v3, v48 offset:7072
	ds_write_b16_d16_hi v3, v48 offset:7344
	global_load_dwordx4 v[52:55], v2, s[12:13] offset:240
	global_load_dwordx4 v[56:59], v2, s[12:13] offset:224
	v_pk_mul_f32 v[48:49], v[104:105], v[50:51] op_sel_hi:[0,1]
	v_pk_mul_f32 v[48:49], v[48:49], v[106:107]
	s_nop 0
	v_cvt_pk_bf16_f32 v48, v48, v49
	ds_write_b16 v3, v48 offset:7616
	ds_write_b16_d16_hi v3, v48 offset:7888
	ds_write_b16 v3, v44 offset:8160
	ds_write_b16_d16_hi v3, v44 offset:8432
	v_pk_mul_f32 v[44:45], v[104:105], v[46:47] op_sel_hi:[0,1]
	v_pk_mul_f32 v[44:45], v[44:45], v[132:133]
	s_nop 0
	v_cvt_pk_bf16_f32 v44, v44, v45
	ds_write_b16 v3, v44 offset:8704
	ds_write_b16_d16_hi v3, v44 offset:8976
	ds_write_b16 v3, v8 offset:9248
	ds_write_b16_d16_hi v3, v8 offset:9520
	v_pk_mul_f32 v[8:9], v[104:105], v[98:99] op_sel_hi:[0,1]
	v_pk_mul_f32 v[8:9], v[8:9], v[128:129]
	v_mov_b32_e32 v45, v2
	v_cvt_pk_bf16_f32 v8, v8, v9
	ds_write_b16 v3, v8 offset:9792
	ds_write_b16_d16_hi v3, v8 offset:10064
	v_pk_mul_f32 v[8:9], v[104:105], v[10:11] op_sel_hi:[0,1]
	v_pk_mul_f32 v[8:9], v[8:9], v[130:131]
	s_nop 0
	v_cvt_pk_bf16_f32 v8, v8, v9
	ds_write_b16 v3, v8 offset:10336
	ds_write_b16_d16_hi v3, v8 offset:10608
	v_pk_mul_f32 v[8:9], v[104:105], v[100:101] op_sel_hi:[0,1]
	v_pk_mul_f32 v[8:9], v[8:9], v[124:125]
	s_nop 0
	v_cvt_pk_bf16_f32 v8, v8, v9
	ds_write_b16 v3, v8 offset:10880
	ds_write_b16_d16_hi v3, v8 offset:11152
	ds_write_b16 v3, v4 offset:11424
	ds_write_b16_d16_hi v3, v4 offset:11696
	v_pk_mul_f32 v[4:5], v[104:105], v[102:103] op_sel_hi:[0,1]
	v_pk_mul_f32 v[4:5], v[4:5], v[120:121]
	s_nop 0
	v_cvt_pk_bf16_f32 v4, v4, v5
	ds_write_b16 v3, v4 offset:11968
	ds_write_b16_d16_hi v3, v4 offset:12240
	v_pk_mul_f32 v[4:5], v[104:105], v[6:7] op_sel_hi:[0,1]
	v_pk_mul_f32 v[4:5], v[4:5], v[122:123]
	s_nop 0
	v_cvt_pk_bf16_f32 v4, v4, v5
	ds_write_b16 v3, v4 offset:12512
	ds_write_b16_d16_hi v3, v4 offset:12784
	v_mov_b32_e32 v4, v88
	v_mov_b32_e32 v5, v90
	v_pk_mul_f32 v[4:5], v[104:105], v[4:5] op_sel_hi:[0,1]
	v_mov_b32_e32 v90, v89
	s_waitcnt vmcnt(2)
	v_pk_mul_f32 v[4:5], v[4:5], v[64:65]
	s_nop 0
	v_cvt_pk_bf16_f32 v4, v4, v5
	ds_write_b16 v3, v4 offset:13056
	ds_write_b16_d16_hi v3, v4 offset:13328
	v_pk_mul_f32 v[4:5], v[104:105], v[90:91] op_sel_hi:[0,1]
	v_pk_mul_f32 v[4:5], v[4:5], v[66:67]
	s_nop 0
	v_cvt_pk_bf16_f32 v4, v4, v5
	ds_write_b16 v3, v4 offset:13600
	ds_write_b16_d16_hi v3, v4 offset:13872
	v_mov_b32_e32 v4, v84
	v_mov_b32_e32 v5, v86
	v_pk_mul_f32 v[4:5], v[104:105], v[4:5] op_sel_hi:[0,1]
	v_pk_mul_f32 v[4:5], v[4:5], v[60:61]
	v_mov_b32_e32 v86, v85
	v_cvt_pk_bf16_f32 v4, v4, v5
	ds_write_b16 v3, v4 offset:14144
	ds_write_b16_d16_hi v3, v4 offset:14416
	v_pk_mul_f32 v[4:5], v[104:105], v[86:87] op_sel_hi:[0,1]
	v_pk_mul_f32 v[4:5], v[4:5], v[62:63]
	s_nop 0
	v_cvt_pk_bf16_f32 v4, v4, v5
	ds_write_b16 v3, v4 offset:14688
	ds_write_b16_d16_hi v3, v4 offset:14960
	v_mov_b32_e32 v4, v80
	v_mov_b32_e32 v5, v82
	v_pk_mul_f32 v[4:5], v[104:105], v[4:5] op_sel_hi:[0,1]
	s_waitcnt vmcnt(0)
; __device__ __forceinline__ unsigned pkbf(float lo, float hi) { typedef float f2_t __attribute__((ext_vector_type(2))); typedef __bf16 b2_t __attribute__((ext_vector_type(2))); f2_t v = {lo, hi}; b2_t b = __builtin_convertvector(v, b2_t); return __builtin_bit_cast(unsigned, b); }
; template <int PAR> __device__ __forceinline__ void attn_sub(const bf16* KS, const bf16* VT, const float* BTg, const float* gq, float sink2, int n, int ti, int hq, const u32x4 w0, const u32x4 w1, bf16* MIX, ss_t* ssb, int lane) {
;     const int fr = lane & 15, fq = lane >> 4; const int qi = 16 * ti + fr, tb = ti - PAR; const int tok = n * 128 + qi;
;     bf16x8 qf[2];
;     { float f0[8], f1[8]; float ss = 0.f;
; #pragma unroll
;       for (int e = 0; e < 4; ++e) { f0[2 * e] = bflo(w0[e]); f0[2 * e + 1] = bfhi(w0[e]); f1[2 * e] = bflo(w1[e]); f1[2 * e + 1] = bfhi(w1[e]);
;           ss += (f0[2 * e] * f0[2 * e] + f0[2 * e + 1] * f0[2 * e + 1]) + (f1[2 * e] * f1[2 * e] + f1[2 * e + 1] * f1[2 * e + 1]); }
;       ss += __shfl_xor(ss, 16); ss += __shfl_xor(ss, 32);
;       const float rs = (0.125f * 1.4426950408889634f) / sqrtf(ss * (1.0f / 64.f) + EPS);
;       const f32x4 a0 = *(const f32x4*)(gq + 8 * fq), a1 = *(const f32x4*)(gq + 8 * fq + 4), b0 = *(const f32x4*)(gq + 32 + 8 * fq), b1 = *(const f32x4*)(gq + 32 + 8 * fq + 4);
; __device__ __forceinline__ void mixer_phase256(const Args& A, int l, int vc, const bf16* Z, bf16* MIX, ss_t* ssa, ss_t* ssb, unsigned char* lds, int tid, int wid, int lane) {
;     ...
;     u32x4 q0[2]; attn_load_q(q0, Z, n, kvh, wid, lane);
;     u32x2 uw[4][4];
; #pragma unroll
;     for (int j = 0; j < 4; ++j)
; #pragma unroll
;         for (int dt = 0; dt < 4; ++dt) uw[j][dt] = *(const u32x2*)(Z + (size_t)((cb + j) * 128 + st) * INW + h * 64 + 16 * dt + 4 * fq);
;     __syncthreads();
;     {
;         bf16x8 bfr[4];
; #pragma unroll
;         for (int ks = 0; ks < 4; ++ks) { float f[8] = {wa[ks][0].x, wa[ks][0].y, wa[ks][0].z, wa[ks][0].w, wa[ks][1].x, wa[ks][1].y, wa[ks][1].z, wa[ks][1].w}; const int s0 = 32 * ks + 8 * fq;
; #pragma unroll
;             for (int e = 0; e < 8; ++e) f[e] = (s0 + e <= st) ? f[e] : 0.f;
;             u32x4 w; w.x = pkbf(f[0], f[1]); w.y = pkbf(f[2], f[3]); w.z = pkbf(f[4], f[5]); w.w = pkbf(f[6], f[7]); bfr[ks] = __builtin_bit_cast(bf16x8, w); }
	v_pk_mul_f32 v[4:5], v[4:5], v[56:57]
	v_mov_b32_e32 v82, v81
	v_cvt_pk_bf16_f32 v4, v4, v5
	ds_write_b16 v3, v4 offset:15232
	ds_write_b16_d16_hi v3, v4 offset:15504
	v_pk_mul_f32 v[4:5], v[104:105], v[82:83] op_sel_hi:[0,1]
	v_pk_mul_f32 v[4:5], v[4:5], v[58:59]
	s_nop 0
	v_cvt_pk_bf16_f32 v4, v4, v5
	ds_write_b16 v3, v4 offset:15776
	ds_write_b16_d16_hi v3, v4 offset:16048
	v_mov_b32_e32 v4, v0
	v_mov_b32_e32 v5, v78
	v_pk_mul_f32 v[4:5], v[104:105], v[4:5] op_sel_hi:[0,1]
	v_pk_mul_f32 v[4:5], v[4:5], v[52:53]
	v_mov_b32_e32 v78, v1
	v_cvt_pk_bf16_f32 v0, v4, v5
	ds_write_b16 v3, v0 offset:16320
	ds_write_b16_d16_hi v3, v0 offset:16592
	v_pk_mul_f32 v[0:1], v[104:105], v[78:79] op_sel_hi:[0,1]
	v_pk_mul_f32 v[0:1], v[0:1], v[54:55]
	s_nop 0
	v_cvt_pk_bf16_f32 v0, v0, v1
	ds_write_b16 v3, v0 offset:16864
	ds_write_b16_d16_hi v3, v0 offset:17136
	v_or_b32_e32 v3, s2, v175
	v_mov_b64_e32 v[0:1], s[82:83]
	v_mad_i64_i32 v[0:1], s[2:3], v3, s85, v[0:1]
	s_lshl_b32 s2, s73, 5
	s_andn2_b32 s2, s2, 63
	v_readlane_b32 s3, v248, 0
	s_add_i32 s2, s2, s3
	v_lshrrev_b32_e32 v3, 1, v113
	s_ashr_i32 s3, s2, 31
	v_and_b32_e32 v3, 24, v3
	v_lshl_add_u64 v[0:1], s[2:3], 1, v[0:1]
	v_lshlrev_b32_e32 v44, 1, v3
	v_lshl_add_u64 v[0:1], v[0:1], 0, v[44:45]
	s_mov_b64 s[2:3], 0x1000
	v_lshl_add_u64 v[8:9], v[0:1], 0, s[2:3]
	s_movk_i32 s2, 0x1000
	v_mov_b32_e32 v200, s73
	v_and_b32_e32 v201, 1, v200
	v_lshrrev_b32_e32 v200, 1, v200
	v_readlane_b32 s100, v249, 63
	v_and_b32_e32 v203, 15, v174
	v_lshl_add_u32 v203, v201, 6, v203
	v_add_u32_e32 v202, s100, v200
	v_readlane_b32 s100, v248, 1
	v_lshrrev_b32_e32 v200, 4, v174
	v_mov_b32_e32 v201, s78
	v_add_u32_e32 v203, s100, v203
	v_mul_u32_u24_e32 v251, 0x1c00, v203
	v_lshl_add_u32 v251, v202, 7, v251
	v_lshl_add_u32 v251, v200, 4, v251
	v_add_u32_e32 v251, 0x18201000, v251
	v_readlane_b32 s100, v250, 28
	v_readlane_b32 s101, v250, 29
	s_nop 4
	global_load_dwordx4 v[116:119], v251, s[100:101]
	global_load_dwordx4 v[120:123], v251, s[100:101] offset:64
	v_add_u32_e32 v251, 0x1c000, v251
	global_load_dwordx4 v[124:127], v251, s[100:101]
	global_load_dwordx4 v[128:131], v251, s[100:101] offset:64
	v_add_u32_e32 v251, 0x1c000, v251
	global_load_dwordx4 v[132:135], v251, s[100:101]
	global_load_dwordx4 v[136:139], v251, s[100:101] offset:64
	v_add_u32_e32 v251, 0x1c000, v251
	global_load_dwordx4 v[140:143], v251, s[100:101]
	global_load_dwordx4 v[144:147], v251, s[100:101] offset:64
	v_readlane_b32 s100, v250, 26
	v_readlane_b32 s101, v250, 27
	v_lshlrev_b32_e32 v203, 5, v200
	v_lshl_add_u32 v203, v201, 8, v203
	s_nop 2
	global_load_dwordx4 v[148:151], v203, s[100:101]
	global_load_dwordx4 v[152:155], v203, s[100:101] offset:16
	global_load_dwordx4 v[156:159], v203, s[100:101] offset:128
	global_load_dwordx4 v[180:183], v203, s[100:101] offset:144
	v_readlane_b32 s100, v250, 32
	v_readlane_b32 s101, v250, 33
	v_lshl_add_u32 v203, v201, 4, v202
	v_lshlrev_b32_e32 v203, 2, v203
	s_nop 2
	global_load_dword v184, v203, s[100:101]
	v_add_co_u32_e32 v0, vcc, s2, v0
	v_readlane_b32 s2, v248, 4
	s_nop 0
	v_addc_co_u32_e32 v1, vcc, 0, v1, vcc
	v_readlane_b32 s3, v248, 5
	global_load_dwordx4 v[4:7], v[0:1], off
	s_nop 0
	global_load_dwordx4 v[8:11], v[8:9], off offset:64
	v_lshl_add_u64 v[0:1], s[2:3], 0, v[76:77]
	v_readlane_b32 s2, v248, 9
	v_cmp_le_i32_e32 vcc, v76, v114
	v_or_b32_e32 v3, 2, v76
	v_add_u32_e32 v78, s2, v114
	v_mad_i64_i32 v[46:47], s[2:3], v78, s85, v[0:1]
	v_readlane_b32 s2, v248, 7
	global_load_dwordx2 v[86:87], v[46:47], off
	global_load_dwordx2 v[84:85], v[46:47], off offset:32
	global_load_dwordx2 v[82:83], v[46:47], off offset:64
	global_load_dwordx2 v[80:81], v[46:47], off offset:96
	v_add_u32_e32 v66, s2, v114
	v_mad_i64_i32 v[46:47], s[2:3], v66, s85, v[0:1]
	v_readlane_b32 s2, v248, 8
	global_load_dwordx2 v[74:75], v[46:47], off
	global_load_dwordx2 v[72:73], v[46:47], off offset:32
	global_load_dwordx2 v[70:71], v[46:47], off offset:64
	global_load_dwordx2 v[68:69], v[46:47], off offset:96
	v_add_u32_e32 v56, s2, v114
	v_mad_i64_i32 v[46:47], s[2:3], v56, s85, v[0:1]
	v_readlane_b32 s2, v248, 10
	global_load_dwordx2 v[64:65], v[46:47], off
	global_load_dwordx2 v[62:63], v[46:47], off offset:32
	global_load_dwordx2 v[60:61], v[46:47], off offset:64
	global_load_dwordx2 v[58:59], v[46:47], off offset:96
	v_add_u32_e32 v46, s2, v114
	v_mad_i64_i32 v[0:1], s[2:3], v46, s85, v[0:1]
	global_load_dwordx2 v[54:55], v[0:1], off
	global_load_dwordx2 v[52:53], v[0:1], off offset:32
	global_load_dwordx2 v[50:51], v[0:1], off offset:64
	global_load_dwordx2 v[48:49], v[0:1], off offset:96
	v_cndmask_b32_e32 v0, 0, v40, vcc
	v_cmp_lt_i32_e32 vcc, v76, v114
	v_or_b32_e32 v40, 3, v76
	s_waitcnt lgkmcnt(0)
	v_cndmask_b32_e32 v1, 0, v41, vcc
	v_cmp_le_i32_e32 vcc, v3, v114
	v_or_b32_e32 v41, 4, v76
	s_barrier
	v_cndmask_b32_e32 v3, 0, v42, vcc
	v_cmp_le_i32_e32 vcc, v40, v114
	s_nop 1
	v_cndmask_b32_e32 v40, 0, v43, vcc
	v_cmp_le_i32_e32 vcc, v41, v114
	s_nop 1
	v_cndmask_b32_e32 v41, 0, v36, vcc
	v_or_b32_e32 v36, 5, v76
	v_cmp_le_i32_e32 vcc, v36, v114
	v_or_b32_e32 v36, 6, v76
	s_nop 0
	v_cndmask_b32_e32 v42, 0, v37, vcc
	v_cmp_le_i32_e32 vcc, v36, v114
	v_or_b32_e32 v36, 7, v76
	v_cvt_pk_bf16_f32 v37, v3, v40
	v_cndmask_b32_e32 v43, 0, v38, vcc
	v_cmp_le_i32_e32 vcc, v36, v114
	v_cvt_pk_bf16_f32 v36, v0, v1
	v_and_b32_e32 v0, 48, v113
	v_cndmask_b32_e32 v39, 0, v39, vcc
	v_add_u32_e32 v47, s14, v0
	v_mul_u32_u24_e32 v0, 0x110, v175
	v_cvt_pk_bf16_f32 v38, v41, v42
	v_cvt_pk_bf16_f32 v39, v43, v39
	s_and_b64 vcc, exec, s[8:9]
	v_add_u32_e32 v88, v47, v0
	s_cbranch_vccz .LBB0_524
	ds_read_b128 v[40:43], v88
	s_waitcnt lgkmcnt(0)
	v_mfma_f32_16x16x32_bf16 v[40:43], v[40:43], v[36:39], 0
	s_branch .LBB0_525

; __device__ __forceinline__ float bflo(unsigned w) { return __uint_as_float(w << 16); }
; __device__ __forceinline__ float bfhi(unsigned w) { return __uint_as_float(w & 0xffff0000u); }
; template <int PAR> __device__ __forceinline__ void attn_sub(const bf16* KS, const bf16* VT, const float* BTg, const float* gq, float sink2, int n, int ti, int hq, const u32x4 w0, const u32x4 w1, bf16* MIX, ss_t* ssb, int lane) {
;     const int fr = lane & 15, fq = lane >> 4; const int qi = 16 * ti + fr, tb = ti - PAR; const int tok = n * 128 + qi;
;     bf16x8 qf[2];
;     { float f0[8], f1[8]; float ss = 0.f;
; #pragma unroll
;       for (int e = 0; e < 4; ++e) { f0[2 * e] = bflo(w0[e]); f0[2 * e + 1] = bfhi(w0[e]); f1[2 * e] = bflo(w1[e]); f1[2 * e + 1] = bfhi(w1[e]);
;           ss += (f0[2 * e] * f0[2 * e] + f0[2 * e + 1] * f0[2 * e + 1]) + (f1[2 * e] * f1[2 * e] + f1[2 * e + 1] * f1[2 * e + 1]); }
;       ss += __shfl_xor(ss, 16); ss += __shfl_xor(ss, 32);
; __device__ __forceinline__ void attn_compute(const Args& A, int l, int n, int kvh, const u32x4 (&q0)[2], const bf16* Z, bf16* MIX, ss_t* ssb, unsigned char* lds, int wid, int lane) {
;     const bf16* KS = (const bf16*)(lds + LDS_KS); const bf16* VT = (const bf16*)(lds + LDS_VT); const float* BT = (const float*)(lds + LDS_BT);
;     const float* gq = A.q_norm_g + l * 64;
;     const int g = wid >> 1, qh = wid & 1, hq = kvh * 4 + g; const int fr = lane & 15, fq = lane >> 4;
;     const float sink2 = A.sinks[l * 16 + hq] * 1.4426950408889634f;
;     const float* BTg = BT + g * 128;
;     u32x4 qc0 = q0[0], qc1 = q0[1];
.LBB0_658:
	s_or_b64 exec, exec, s[2:3]
	v_readlane_b32 s100, v250, 28
	v_readlane_b32 s101, v250, 29
	v_readlane_b32 s24, v249, 63
	v_readlane_b32 s23, v248, 1
	s_lshr_b32 s20, s73, 1
	s_and_b32 s21, s73, 1
	s_lshl_b32 s26, s21, 2
	v_and_b32_e32 v200, 15, v174
	v_lshrrev_b32_e32 v201, 4, v174
	s_add_i32 s22, s24, s20
	s_cmp_gt_i32 s23, 0
	s_cselect_b64 s[36:37], -1, 0
	v_lshlrev_b32_e32 v202, 2, v201
	v_add_u32_e32 v203, 0, v202
	v_cmp_gt_i32_e64 s[40:41], v203, v200
	v_add_u32_e32 v203, 1, v202
	v_cmp_gt_i32_e64 s[42:43], v203, v200
	v_add_u32_e32 v203, 2, v202
	v_cmp_gt_i32_e64 s[44:45], v203, v200
	v_add_u32_e32 v203, 3, v202
	v_cmp_gt_i32_e64 s[46:47], v203, v200
	v_cmp_eq_u32_e64 s[56:57], 0, v201
	v_mov_b32_e32 v203, s21
	v_lshl_add_u32 v185, v203, 6, v200
	v_mul_u32_u24_e32 v185, 0x90, v185
	v_lshl_add_u32 v185, v201, 4, v185
	v_lshlrev_b32_e32 v186, 2, v200
	v_lshlrev_b32_e32 v0, 4, v201
	v_sub_u32_e32 v186, v186, v0
	s_lshl_b32 s27, s20, 9
	s_add_i32 s27, s27, 0x113f4
	v_add_u32_e32 v186, s27, v186
	v_mul_u32_u24_e32 v187, 0x210, v200
	v_lshl_add_u32 v187, v203, 7, v187
	v_lshl_add_u32 v187, v201, 3, v187
	v_add_u32_e32 v187, 0x9000, v187
	v_add_u32_e32 v188, 0x2100, v187
	v_add_u32_e32 v189, 0x4200, v187
	v_add_u32_e32 v190, 0x6300, v187
	v_lshl_add_u32 v0, v203, 6, v200
	v_add_u32_e32 v0, s23, v0
	v_lshlrev_b32_e32 v191, 12, v0
	s_lshl_b32 s27, s22, 7
	s_add_i32 s27, s27, 0x1ba00800
	v_add_u32_e32 v191, s27, v191
	v_lshl_add_u32 v191, v201, 3, v191
	s_add_i32 s27, s78, 13
	s_lshl_b32 s27, s27, 16
	v_lshl_add_u32 v192, v0, 3, s27
	v_xor_b32_e32 v193, 16, v174
	v_lshlrev_b32_e32 v193, 2, v193
	v_xor_b32_e32 v194, 32, v174
	v_lshlrev_b32_e32 v194, 2, v194
	v_mov_b32_e32 v195, 0xf149f2ca
	v_mul_f32_e32 v184, 0x3fb8aa3b, v184
	v_lshlrev_b32_e32 v4, 16, v116
	v_and_b32_e32 v5, 0xffff0000, v116
	v_lshlrev_b32_e32 v6, 16, v117
	v_and_b32_e32 v7, 0xffff0000, v117
	v_lshlrev_b32_e32 v8, 16, v118
	v_and_b32_e32 v9, 0xffff0000, v118
	v_lshlrev_b32_e32 v10, 16, v119
	v_and_b32_e32 v11, 0xffff0000, v119
	v_lshlrev_b32_e32 v12, 16, v120
	v_and_b32_e32 v13, 0xffff0000, v120
	v_lshlrev_b32_e32 v14, 16, v121
	v_and_b32_e32 v15, 0xffff0000, v121
	v_lshlrev_b32_e32 v16, 16, v122
	v_and_b32_e32 v17, 0xffff0000, v122
	v_lshlrev_b32_e32 v18, 16, v123
	v_and_b32_e32 v19, 0xffff0000, v123
	v_pk_mul_f32 v[78:79], v[4:5], v[4:5]
	v_pk_fma_f32 v[78:79], v[6:7], v[6:7], v[78:79]
	v_pk_fma_f32 v[78:79], v[8:9], v[8:9], v[78:79]
	v_pk_fma_f32 v[78:79], v[10:11], v[10:11], v[78:79]
	v_pk_fma_f32 v[78:79], v[12:13], v[12:13], v[78:79]
	v_pk_fma_f32 v[78:79], v[14:15], v[14:15], v[78:79]
	v_pk_fma_f32 v[78:79], v[16:17], v[16:17], v[78:79]
	v_pk_fma_f32 v[78:79], v[18:19], v[18:19], v[78:79]
	v_add_f32_e32 v45, v78, v79
	v_lshlrev_b32_e32 v20, 16, v124
	v_and_b32_e32 v21, 0xffff0000, v124
	v_lshlrev_b32_e32 v22, 16, v125
	v_and_b32_e32 v23, 0xffff0000, v125
	v_lshlrev_b32_e32 v24, 16, v126
	v_and_b32_e32 v25, 0xffff0000, v126
	v_lshlrev_b32_e32 v26, 16, v127
	v_and_b32_e32 v27, 0xffff0000, v127
	v_lshlrev_b32_e32 v28, 16, v128
	v_and_b32_e32 v29, 0xffff0000, v128
	v_lshlrev_b32_e32 v30, 16, v129
	v_and_b32_e32 v31, 0xffff0000, v129
	v_lshlrev_b32_e32 v32, 16, v130
	v_and_b32_e32 v33, 0xffff0000, v130
	v_lshlrev_b32_e32 v34, 16, v131
	v_and_b32_e32 v35, 0xffff0000, v131
	v_pk_mul_f32 v[80:81], v[20:21], v[20:21]
	v_pk_fma_f32 v[80:81], v[22:23], v[22:23], v[80:81]
	v_pk_fma_f32 v[80:81], v[24:25], v[24:25], v[80:81]
	v_pk_fma_f32 v[80:81], v[26:27], v[26:27], v[80:81]
	v_pk_fma_f32 v[80:81], v[28:29], v[28:29], v[80:81]
	v_pk_fma_f32 v[80:81], v[30:31], v[30:31], v[80:81]
	v_pk_fma_f32 v[80:81], v[32:33], v[32:33], v[80:81]
	v_pk_fma_f32 v[80:81], v[34:35], v[34:35], v[80:81]
	v_add_f32_e32 v46, v80, v81
	v_lshlrev_b32_e32 v212, 16, v132
	v_and_b32_e32 v213, 0xffff0000, v132
	v_lshlrev_b32_e32 v214, 16, v133
	v_and_b32_e32 v215, 0xffff0000, v133
	v_lshlrev_b32_e32 v216, 16, v134
	v_and_b32_e32 v217, 0xffff0000, v134
	v_lshlrev_b32_e32 v218, 16, v135
	v_and_b32_e32 v219, 0xffff0000, v135
	v_lshlrev_b32_e32 v220, 16, v136
	v_and_b32_e32 v221, 0xffff0000, v136
	v_lshlrev_b32_e32 v222, 16, v137
	v_and_b32_e32 v223, 0xffff0000, v137
	v_lshlrev_b32_e32 v224, 16, v138
	v_and_b32_e32 v225, 0xffff0000, v138
	v_lshlrev_b32_e32 v226, 16, v139
	v_and_b32_e32 v227, 0xffff0000, v139
	v_pk_mul_f32 v[96:97], v[212:213], v[212:213]
	v_pk_fma_f32 v[96:97], v[214:215], v[214:215], v[96:97]
	v_pk_fma_f32 v[96:97], v[216:217], v[216:217], v[96:97]
	v_pk_fma_f32 v[96:97], v[218:219], v[218:219], v[96:97]
	v_pk_fma_f32 v[96:97], v[220:221], v[220:221], v[96:97]
	v_pk_fma_f32 v[96:97], v[222:223], v[222:223], v[96:97]
	v_pk_fma_f32 v[96:97], v[224:225], v[224:225], v[96:97]
	v_pk_fma_f32 v[96:97], v[226:227], v[226:227], v[96:97]
	v_add_f32_e32 v47, v96, v97
	v_lshlrev_b32_e32 v228, 16, v140
	v_and_b32_e32 v229, 0xffff0000, v140
	v_lshlrev_b32_e32 v230, 16, v141
	v_and_b32_e32 v231, 0xffff0000, v141
	v_lshlrev_b32_e32 v232, 16, v142
	v_and_b32_e32 v233, 0xffff0000, v142
	v_lshlrev_b32_e32 v234, 16, v143
	v_and_b32_e32 v235, 0xffff0000, v143
	v_lshlrev_b32_e32 v236, 16, v144
	v_and_b32_e32 v237, 0xffff0000, v144
	v_lshlrev_b32_e32 v238, 16, v145
	v_and_b32_e32 v239, 0xffff0000, v145
	v_lshlrev_b32_e32 v240, 16, v146
	v_and_b32_e32 v241, 0xffff0000, v146
	v_lshlrev_b32_e32 v242, 16, v147
	v_and_b32_e32 v243, 0xffff0000, v147
	v_pk_mul_f32 v[98:99], v[228:229], v[228:229]
	v_pk_fma_f32 v[98:99], v[230:231], v[230:231], v[98:99]
	v_pk_fma_f32 v[98:99], v[232:233], v[232:233], v[98:99]
	v_pk_fma_f32 v[98:99], v[234:235], v[234:235], v[98:99]
	v_pk_fma_f32 v[98:99], v[236:237], v[236:237], v[98:99]
	v_pk_fma_f32 v[98:99], v[238:239], v[238:239], v[98:99]
	v_pk_fma_f32 v[98:99], v[240:241], v[240:241], v[98:99]
	v_pk_fma_f32 v[98:99], v[242:243], v[242:243], v[98:99]
	v_add_f32_e32 v76, v98, v99
	ds_bpermute_b32 v0, v193, v45
	ds_bpermute_b32 v1, v193, v46
	ds_bpermute_b32 v3, v193, v47
	ds_bpermute_b32 v100, v193, v76
	s_waitcnt lgkmcnt(0)
; __device__ __forceinline__ unsigned pkbf(float lo, float hi) { typedef float f2_t __attribute__((ext_vector_type(2))); typedef __bf16 b2_t __attribute__((ext_vector_type(2))); f2_t v = {lo, hi}; b2_t b = __builtin_convertvector(v, b2_t); return __builtin_bit_cast(unsigned, b); }
; template <int PAR> __device__ __forceinline__ void attn_sub(const bf16* KS, const bf16* VT, const float* BTg, const float* gq, float sink2, int n, int ti, int hq, const u32x4 w0, const u32x4 w1, bf16* MIX, ss_t* ssb, int lane) {
;     ...
;       ss += __shfl_xor(ss, 16); ss += __shfl_xor(ss, 32);
;       const float rs = (0.125f * 1.4426950408889634f) / sqrtf(ss * (1.0f / 64.f) + EPS);
;       const f32x4 a0 = *(const f32x4*)(gq + 8 * fq), a1 = *(const f32x4*)(gq + 8 * fq + 4), b0 = *(const f32x4*)(gq + 32 + 8 * fq), b1 = *(const f32x4*)(gq + 32 + 8 * fq + 4);
;       u32x4 p0, p1;
;       p0.x = pkbf(f0[0] * rs * a0.x, f0[1] * rs * a0.y); p0.y = pkbf(f0[2] * rs * a0.z, f0[3] * rs * a0.w); p0.z = pkbf(f0[4] * rs * a1.x, f0[5] * rs * a1.y); p0.w = pkbf(f0[6] * rs * a1.z, f0[7] * rs * a1.w);
;       p1.x = pkbf(f1[0] * rs * b0.x, f1[1] * rs * b0.y); p1.y = pkbf(f1[2] * rs * b0.z, f1[3] * rs * b0.w); p1.z = pkbf(f1[4] * rs * b1.x, f1[5] * rs * b1.y); p1.w = pkbf(f1[6] * rs * b1.z, f1[7] * rs * b1.w);
;       qf[0] = __builtin_bit_cast(bf16x8, p0); qf[1] = __builtin_bit_cast(bf16x8, p1); }
;     const int e0 = 4 * fq - fr;
;     const float* bp = BTg + (128 - 16 * 8 - 3 - e0);
;     ...
;             const float v = valid ? acc[r] + bp[16 * (8 - rel) + (3 - r)] : -1e30f; acc[r] = v; mx = fmaxf(mx, v); }
	v_add_f32_e32 v45, v45, v0
	v_add_f32_e32 v46, v46, v1
	v_add_f32_e32 v47, v47, v3
	v_add_f32_e32 v76, v76, v100
	ds_bpermute_b32 v0, v194, v45
	ds_bpermute_b32 v1, v194, v46
	ds_bpermute_b32 v3, v194, v47
	ds_bpermute_b32 v100, v194, v76
	s_waitcnt lgkmcnt(0)
	v_add_f32_e32 v45, v45, v0
	v_add_f32_e32 v46, v46, v1
	v_add_f32_e32 v47, v47, v3
	v_add_f32_e32 v76, v76, v100
	v_fmamk_f32 v45, v45, 0x3c800000, v205
	v_fmamk_f32 v46, v46, 0x3c800000, v205
	v_fmamk_f32 v47, v47, 0x3c800000, v205
	v_fmamk_f32 v76, v76, 0x3c800000, v205
	v_rsq_f32_e32 v45, v45
	v_rsq_f32_e32 v46, v46
	v_rsq_f32_e32 v47, v47
	v_rsq_f32_e32 v76, v76
	s_nop 0
	v_mul_f32_e32 v78, 0x3e38aa3b, v45
	v_mul_f32_e32 v80, 0x3e38aa3b, v46
	v_mul_f32_e32 v96, 0x3e38aa3b, v47
	v_mul_f32_e32 v98, 0x3e38aa3b, v76
	v_pk_mul_f32 v[4:5], v[78:79], v[4:5] op_sel_hi:[0,1]
	v_pk_mul_f32 v[4:5], v[4:5], v[148:149]
	v_cvt_pk_bf16_f32 v116, v4, v5
	v_pk_mul_f32 v[6:7], v[78:79], v[6:7] op_sel_hi:[0,1]
	v_pk_mul_f32 v[6:7], v[6:7], v[150:151]
	v_cvt_pk_bf16_f32 v117, v6, v7
	v_pk_mul_f32 v[8:9], v[78:79], v[8:9] op_sel_hi:[0,1]
	v_pk_mul_f32 v[8:9], v[8:9], v[152:153]
	v_cvt_pk_bf16_f32 v118, v8, v9
	v_pk_mul_f32 v[10:11], v[78:79], v[10:11] op_sel_hi:[0,1]
	v_pk_mul_f32 v[10:11], v[10:11], v[154:155]
	v_cvt_pk_bf16_f32 v119, v10, v11
	v_pk_mul_f32 v[12:13], v[78:79], v[12:13] op_sel_hi:[0,1]
	v_pk_mul_f32 v[12:13], v[12:13], v[156:157]
	v_cvt_pk_bf16_f32 v120, v12, v13
	v_pk_mul_f32 v[14:15], v[78:79], v[14:15] op_sel_hi:[0,1]
	v_pk_mul_f32 v[14:15], v[14:15], v[158:159]
	v_cvt_pk_bf16_f32 v121, v14, v15
	v_pk_mul_f32 v[16:17], v[78:79], v[16:17] op_sel_hi:[0,1]
	v_pk_mul_f32 v[16:17], v[16:17], v[180:181]
	v_cvt_pk_bf16_f32 v122, v16, v17
	v_pk_mul_f32 v[18:19], v[78:79], v[18:19] op_sel_hi:[0,1]
	v_pk_mul_f32 v[18:19], v[18:19], v[182:183]
	v_cvt_pk_bf16_f32 v123, v18, v19
	v_pk_mul_f32 v[20:21], v[80:81], v[20:21] op_sel_hi:[0,1]
	v_pk_mul_f32 v[20:21], v[20:21], v[148:149]
	v_cvt_pk_bf16_f32 v124, v20, v21
	v_pk_mul_f32 v[22:23], v[80:81], v[22:23] op_sel_hi:[0,1]
	v_pk_mul_f32 v[22:23], v[22:23], v[150:151]
	v_cvt_pk_bf16_f32 v125, v22, v23
	v_pk_mul_f32 v[24:25], v[80:81], v[24:25] op_sel_hi:[0,1]
	v_pk_mul_f32 v[24:25], v[24:25], v[152:153]
	v_cvt_pk_bf16_f32 v126, v24, v25
	v_pk_mul_f32 v[26:27], v[80:81], v[26:27] op_sel_hi:[0,1]
	v_pk_mul_f32 v[26:27], v[26:27], v[154:155]
	v_cvt_pk_bf16_f32 v127, v26, v27
	v_pk_mul_f32 v[28:29], v[80:81], v[28:29] op_sel_hi:[0,1]
	v_pk_mul_f32 v[28:29], v[28:29], v[156:157]
	v_cvt_pk_bf16_f32 v128, v28, v29
	v_pk_mul_f32 v[30:31], v[80:81], v[30:31] op_sel_hi:[0,1]
	v_pk_mul_f32 v[30:31], v[30:31], v[158:159]
	v_cvt_pk_bf16_f32 v129, v30, v31
	v_pk_mul_f32 v[32:33], v[80:81], v[32:33] op_sel_hi:[0,1]
	v_pk_mul_f32 v[32:33], v[32:33], v[180:181]
	v_cvt_pk_bf16_f32 v130, v32, v33
	v_pk_mul_f32 v[34:35], v[80:81], v[34:35] op_sel_hi:[0,1]
	v_pk_mul_f32 v[34:35], v[34:35], v[182:183]
	v_cvt_pk_bf16_f32 v131, v34, v35
	v_pk_mul_f32 v[212:213], v[96:97], v[212:213] op_sel_hi:[0,1]
	v_pk_mul_f32 v[212:213], v[212:213], v[148:149]
	v_cvt_pk_bf16_f32 v132, v212, v213
	v_pk_mul_f32 v[214:215], v[96:97], v[214:215] op_sel_hi:[0,1]
	v_pk_mul_f32 v[214:215], v[214:215], v[150:151]
	v_cvt_pk_bf16_f32 v133, v214, v215
	v_pk_mul_f32 v[216:217], v[96:97], v[216:217] op_sel_hi:[0,1]
	v_pk_mul_f32 v[216:217], v[216:217], v[152:153]
	v_cvt_pk_bf16_f32 v134, v216, v217
	v_pk_mul_f32 v[218:219], v[96:97], v[218:219] op_sel_hi:[0,1]
	v_pk_mul_f32 v[218:219], v[218:219], v[154:155]
	v_cvt_pk_bf16_f32 v135, v218, v219
	v_pk_mul_f32 v[220:221], v[96:97], v[220:221] op_sel_hi:[0,1]
	v_pk_mul_f32 v[220:221], v[220:221], v[156:157]
	v_cvt_pk_bf16_f32 v136, v220, v221
	v_pk_mul_f32 v[222:223], v[96:97], v[222:223] op_sel_hi:[0,1]
	v_pk_mul_f32 v[222:223], v[222:223], v[158:159]
	v_cvt_pk_bf16_f32 v137, v222, v223
	v_pk_mul_f32 v[224:225], v[96:97], v[224:225] op_sel_hi:[0,1]
	v_pk_mul_f32 v[224:225], v[224:225], v[180:181]
	v_cvt_pk_bf16_f32 v138, v224, v225
	v_pk_mul_f32 v[226:227], v[96:97], v[226:227] op_sel_hi:[0,1]
	v_pk_mul_f32 v[226:227], v[226:227], v[182:183]
	v_cvt_pk_bf16_f32 v139, v226, v227
	v_pk_mul_f32 v[228:229], v[98:99], v[228:229] op_sel_hi:[0,1]
	v_pk_mul_f32 v[228:229], v[228:229], v[148:149]
	v_cvt_pk_bf16_f32 v140, v228, v229
	v_pk_mul_f32 v[230:231], v[98:99], v[230:231] op_sel_hi:[0,1]
	v_pk_mul_f32 v[230:231], v[230:231], v[150:151]
	v_cvt_pk_bf16_f32 v141, v230, v231
	v_pk_mul_f32 v[232:233], v[98:99], v[232:233] op_sel_hi:[0,1]
	v_pk_mul_f32 v[232:233], v[232:233], v[152:153]
	v_cvt_pk_bf16_f32 v142, v232, v233
	v_pk_mul_f32 v[234:235], v[98:99], v[234:235] op_sel_hi:[0,1]
	v_pk_mul_f32 v[234:235], v[234:235], v[154:155]
	v_cvt_pk_bf16_f32 v143, v234, v235
	v_pk_mul_f32 v[236:237], v[98:99], v[236:237] op_sel_hi:[0,1]
	v_pk_mul_f32 v[236:237], v[236:237], v[156:157]
	v_cvt_pk_bf16_f32 v144, v236, v237
	v_pk_mul_f32 v[238:239], v[98:99], v[238:239] op_sel_hi:[0,1]
	v_pk_mul_f32 v[238:239], v[238:239], v[158:159]
	v_cvt_pk_bf16_f32 v145, v238, v239
	v_pk_mul_f32 v[240:241], v[98:99], v[240:241] op_sel_hi:[0,1]
	v_pk_mul_f32 v[240:241], v[240:241], v[180:181]
	v_cvt_pk_bf16_f32 v146, v240, v241
	v_pk_mul_f32 v[242:243], v[98:99], v[242:243] op_sel_hi:[0,1]
	v_pk_mul_f32 v[242:243], v[242:243], v[182:183]
	v_cvt_pk_bf16_f32 v147, v242, v243
	ds_read2_b32 v[84:85], v186 offset0:128 offset1:129
	ds_read2_b32 v[86:87], v186 offset0:130 offset1:131
	ds_read2_b32 v[88:89], v186 offset0:112 offset1:113
	ds_read2_b32 v[90:91], v186 offset0:114 offset1:115
	ds_read2_b32 v[92:93], v186 offset0:96 offset1:97
	ds_read2_b32 v[94:95], v186 offset0:98 offset1:99
	ds_read2_b32 v[96:97], v186 offset0:80 offset1:81
	ds_read2_b32 v[98:99], v186 offset0:82 offset1:83
	ds_read2_b32 v[40:41], v186 offset0:64 offset1:65
	ds_read2_b32 v[42:43], v186 offset0:66 offset1:67
	s_waitcnt lgkmcnt(0)
; #define MFMA16(a, b, c) __builtin_amdgcn_mfma_f32_16x16x32_bf16((a), (b), (c), 0, 0, 0)
; template <int PAR> __device__ __forceinline__ void attn_sub(const bf16* KS, const bf16* VT, const float* BTg, const float* gq, float sink2, int n, int ti, int hq, const u32x4 w0, const u32x4 w1, bf16* MIX, ss_t* ssb, int lane) {
;     ...
;     for (int t = 0; t < 10; ++t) {
;         constexpr int dummy = 0; (void)dummy;
;         const int rel = t - PAR;
;         if (rel < 0 || rel > 8) { sc[t] = (f32x4){0.f, 0.f, 0.f, 0.f}; continue; }
;         const bf16* kp = KS + (16 * (tb + t) + fr) * KS_STRIDE + 8 * fq;
;         const bf16x8 k0 = *(const bf16x8*)kp, k1 = *(const bf16x8*)(kp + 32);
;         f32x4 acc = (f32x4){0.f, 0.f, 0.f, 0.f};
;         acc = MFMA16(k0, qf[0], acc); acc = MFMA16(k1, qf[1], acc);
;         const bool tv = (n > 0) || (tb + t >= 8);
; #pragma unroll
;         for (int r = 0; r < 4; ++r) { bool valid = tv; if (rel == 0) valid = valid && (e0 + r >= 1); if (rel == 8) valid = valid && (e0 + r <= 0);
;             const float v = valid ? acc[r] + bp[16 * (8 - rel) + (3 - r)] : -1e30f; acc[r] = v; mx = fmaxf(mx, v); }
;         sc[t] = acc;
;     }
	ds_read2_b32 v[72:73], v186 offset0:48 offset1:49
	ds_read2_b32 v[74:75], v186 offset0:50 offset1:51
	ds_read2_b32 v[148:149], v186 offset0:32 offset1:33
	ds_read2_b32 v[150:151], v186 offset0:34 offset1:35
	ds_read2_b32 v[152:153], v186 offset0:16 offset1:17
	ds_read2_b32 v[154:155], v186 offset0:18 offset1:19
	ds_read2_b32 v[156:157], v186 offset0:0 offset1:1
	ds_read2_b32 v[158:159], v186 offset0:2 offset1:3
	s_waitcnt lgkmcnt(0)
	ds_read_b128 v[212:215], v185 offset:0
	ds_read_b128 v[216:219], v185 offset:64
	ds_read_b128 v[220:223], v185 offset:2304
	ds_read_b128 v[224:227], v185 offset:2368
	ds_read_b128 v[228:231], v185 offset:4608
	ds_read_b128 v[232:235], v185 offset:4672
	ds_read_b128 v[48:51], v185 offset:6912
	ds_read_b128 v[52:55], v185 offset:6976
	ds_read_b128 v[56:59], v185 offset:9216
	ds_read_b128 v[60:63], v185 offset:9280
	ds_read_b128 v[64:67], v185 offset:11520
	ds_read_b128 v[68:71], v185 offset:11584
	s_waitcnt lgkmcnt(6)
	v_mfma_f32_16x16x32_bf16 v[4:7], v[212:215], v[116:119], 0
	v_mfma_f32_16x16x32_bf16 v[8:11], v[220:223], v[116:119], 0
	v_mfma_f32_16x16x32_bf16 v[12:15], v[228:231], v[116:119], 0
	v_mfma_f32_16x16x32_bf16 v[4:7], v[216:219], v[120:123], v[4:7]
	v_mfma_f32_16x16x32_bf16 v[8:11], v[224:227], v[120:123], v[8:11]
	v_mfma_f32_16x16x32_bf16 v[12:15], v[232:235], v[120:123], v[12:15]
	ds_read_b128 v[212:215], v185 offset:13824
	ds_read_b128 v[216:219], v185 offset:13888
	ds_read_b128 v[220:223], v185 offset:16128
	ds_read_b128 v[224:227], v185 offset:16192
	ds_read_b128 v[228:231], v185 offset:18432
	ds_read_b128 v[232:235], v185 offset:18496
	s_waitcnt lgkmcnt(6)
	v_mfma_f32_16x16x32_bf16 v[16:19], v[48:51], v[116:119], 0
	v_mfma_f32_16x16x32_bf16 v[20:23], v[56:59], v[116:119], 0
	v_mfma_f32_16x16x32_bf16 v[24:27], v[64:67], v[116:119], 0
	v_mfma_f32_16x16x32_bf16 v[16:19], v[52:55], v[120:123], v[16:19]
	v_mfma_f32_16x16x32_bf16 v[20:23], v[60:63], v[120:123], v[20:23]
	v_mfma_f32_16x16x32_bf16 v[24:27], v[68:71], v[120:123], v[24:27]
	s_add_i32 s27, s26, 0
	s_cmp_ge_i32 s27, 8
	s_cselect_b64 s[2:3], -1, 0
	s_or_b64 s[2:3], s[2:3], s[36:37]
	s_and_b64 s[4:5], s[2:3], s[40:41]
	s_and_b64 s[6:7], s[2:3], s[42:43]
	s_and_b64 s[8:9], s[2:3], s[44:45]
	s_and_b64 s[10:11], s[2:3], s[46:47]
	v_add_f32_e32 v4, v4, v87
	v_add_f32_e32 v5, v5, v86
	v_add_f32_e32 v6, v6, v85
	v_add_f32_e32 v7, v7, v84
	v_cndmask_b32_e64 v4, v195, v4, s[4:5]
	v_cndmask_b32_e64 v5, v195, v5, s[6:7]
	v_cndmask_b32_e64 v6, v195, v6, s[8:9]
	v_cndmask_b32_e64 v7, v195, v7, s[10:11]
	s_add_i32 s27, s26, 1
	s_cmp_ge_i32 s27, 8
	s_cselect_b64 s[12:13], -1, 0
	s_or_b64 s[12:13], s[12:13], s[36:37]
	v_add_f32_e32 v8, v8, v91
	v_add_f32_e32 v9, v9, v90
	v_add_f32_e32 v10, v10, v89
	v_add_f32_e32 v11, v11, v88
	v_cndmask_b32_e64 v8, v195, v8, s[12:13]
	v_cndmask_b32_e64 v9, v195, v9, s[12:13]
	v_cndmask_b32_e64 v10, v195, v10, s[12:13]
	v_cndmask_b32_e64 v11, v195, v11, s[12:13]
	s_add_i32 s27, s26, 2
	s_cmp_ge_i32 s27, 8
	s_cselect_b64 s[2:3], -1, 0
	s_or_b64 s[2:3], s[2:3], s[36:37]
	v_add_f32_e32 v12, v12, v95
	v_add_f32_e32 v13, v13, v94
	v_add_f32_e32 v14, v14, v93
	v_add_f32_e32 v15, v15, v92
	v_cndmask_b32_e64 v12, v195, v12, s[2:3]
	v_cndmask_b32_e64 v13, v195, v13, s[2:3]
	v_cndmask_b32_e64 v14, v195, v14, s[2:3]
	v_cndmask_b32_e64 v15, v195, v15, s[2:3]
	s_waitcnt lgkmcnt(0)
	v_mfma_f32_16x16x32_bf16 v[28:31], v[212:215], v[116:119], 0
	v_mfma_f32_16x16x32_bf16 v[32:35], v[220:223], v[116:119], 0
	v_mfma_f32_16x16x32_bf16 v[36:39], v[228:231], v[116:119], 0
	v_mfma_f32_16x16x32_bf16 v[28:31], v[216:219], v[120:123], v[28:31]
	v_mfma_f32_16x16x32_bf16 v[32:35], v[224:227], v[120:123], v[32:35]
	v_mfma_f32_16x16x32_bf16 v[36:39], v[232:235], v[120:123], v[36:39]
	ds_read2_b64 v[212:215], v187 offset0:0 offset1:4
	ds_read2_b64 v[216:219], v188 offset0:0 offset1:4
	ds_read2_b64 v[220:223], v189 offset0:0 offset1:4
	ds_read2_b64 v[224:227], v190 offset0:0 offset1:4
	ds_read2_b64 v[228:231], v187 offset0:8 offset1:12
	ds_read2_b64 v[232:235], v188 offset0:8 offset1:12
	ds_read2_b64 v[236:239], v189 offset0:8 offset1:12
	ds_read2_b64 v[240:243], v190 offset0:8 offset1:12
	s_add_i32 s27, s26, 3
	s_cmp_ge_i32 s27, 8
	s_cselect_b64 s[12:13], -1, 0
	s_or_b64 s[12:13], s[12:13], s[36:37]
	v_add_f32_e32 v16, v16, v99
	v_add_f32_e32 v17, v17, v98
	v_add_f32_e32 v18, v18, v97
	v_add_f32_e32 v19, v19, v96
	v_cndmask_b32_e64 v16, v195, v16, s[12:13]
	v_cndmask_b32_e64 v17, v195, v17, s[12:13]
	v_cndmask_b32_e64 v18, v195, v18, s[12:13]
	v_cndmask_b32_e64 v19, v195, v19, s[12:13]
	s_add_i32 s27, s26, 4
	s_cmp_ge_i32 s27, 8
	s_cselect_b64 s[2:3], -1, 0
	s_or_b64 s[2:3], s[2:3], s[36:37]
	v_add_f32_e32 v20, v20, v43
	v_add_f32_e32 v21, v21, v42
	v_add_f32_e32 v22, v22, v41
	v_add_f32_e32 v23, v23, v40
	v_cndmask_b32_e64 v20, v195, v20, s[2:3]
	v_cndmask_b32_e64 v21, v195, v21, s[2:3]
	v_cndmask_b32_e64 v22, v195, v22, s[2:3]
	v_cndmask_b32_e64 v23, v195, v23, s[2:3]
	s_add_i32 s27, s26, 5
	s_cmp_ge_i32 s27, 8
	s_cselect_b64 s[12:13], -1, 0
	s_or_b64 s[12:13], s[12:13], s[36:37]
	v_add_f32_e32 v24, v24, v75
	v_add_f32_e32 v25, v25, v74
	v_add_f32_e32 v26, v26, v73
	v_add_f32_e32 v27, v27, v72
	v_cndmask_b32_e64 v24, v195, v24, s[12:13]
	v_cndmask_b32_e64 v25, v195, v25, s[12:13]
	v_cndmask_b32_e64 v26, v195, v26, s[12:13]
	v_cndmask_b32_e64 v27, v195, v27, s[12:13]
	s_add_i32 s27, s26, 6
	s_cmp_ge_i32 s27, 8
	s_cselect_b64 s[2:3], -1, 0
	s_or_b64 s[2:3], s[2:3], s[36:37]
	v_add_f32_e32 v28, v28, v151
	v_add_f32_e32 v29, v29, v150
	v_add_f32_e32 v30, v30, v149
	v_add_f32_e32 v31, v31, v148
	v_cndmask_b32_e64 v28, v195, v28, s[2:3]
; __device__ __forceinline__ unsigned pkbf(float lo, float hi) { typedef float f2_t __attribute__((ext_vector_type(2))); typedef __bf16 b2_t __attribute__((ext_vector_type(2))); f2_t v = {lo, hi}; b2_t b = __builtin_convertvector(v, b2_t); return __builtin_bit_cast(unsigned, b); }
; #define MFMA16(a, b, c) __builtin_amdgcn_mfma_f32_16x16x32_bf16((a), (b), (c), 0, 0, 0)
; template <int PAR> __device__ __forceinline__ void attn_sub(const bf16* KS, const bf16* VT, const float* BTg, const float* gq, float sink2, int n, int ti, int hq, const u32x4 w0, const u32x4 w1, bf16* MIX, ss_t* ssb, int lane) {
;     ...
;         for (int r = 0; r < 4; ++r) { bool valid = tv; if (rel == 0) valid = valid && (e0 + r >= 1); if (rel == 8) valid = valid && (e0 + r <= 0);
;             const float v = valid ? acc[r] + bp[16 * (8 - rel) + (3 - r)] : -1e30f; acc[r] = v; mx = fmaxf(mx, v); }
;         sc[t] = acc;
;     }
;     mx = fmaxf(mx, __shfl_xor(mx, 16)); mx = fmaxf(mx, __shfl_xor(mx, 32));
;     float lsum = 0.f;
; #pragma unroll
;     for (int t = 0; t < 10; ++t) { const int rel = t - PAR; if (rel < 0 || rel > 8) continue;
; #pragma unroll
;         for (int r = 0; r < 4; ++r) { const float p = __builtin_amdgcn_exp2f(sc[t][r] - mx); sc[t][r] = p; lsum += p; } }
;     lsum += __shfl_xor(lsum, 16); lsum += __shfl_xor(lsum, 32);
;     lsum += __builtin_amdgcn_exp2f(sink2 - mx);
;     const float rl = 1.0f / lsum;
;     f32x4 o[4];
; #pragma unroll
;     for (int dt = 0; dt < 4; ++dt) o[dt] = (f32x4){0.f, 0.f, 0.f, 0.f};
; #pragma unroll
;     for (int p = 0; p < 5; ++p) {
;         u32x4 pw; pw.x = pkbf(sc[2 * p][0], sc[2 * p][1]); pw.y = pkbf(sc[2 * p][2], sc[2 * p][3]); pw.z = pkbf(sc[2 * p + 1][0], sc[2 * p + 1][1]); pw.w = pkbf(sc[2 * p + 1][2], sc[2 * p + 1][3]);
;         const bf16x8 pb = __builtin_bit_cast(bf16x8, pw);
; #pragma unroll
;         for (int dt = 0; dt < 4; ++dt) {
;             const bf16* vp = VT + (16 * dt + fr) * VT_STRIDE + 16 * (tb + 2 * p) + 4 * fq;
;             const u32x2 lo = *(const u32x2*)vp, hi = *(const u32x2*)(vp + 16);
;             const u32x4 va = (u32x4){lo.x, lo.y, hi.x, hi.y};
;             o[dt] = MFMA16(__builtin_bit_cast(bf16x8, va), pb, o[dt]);
	v_cndmask_b32_e64 v29, v195, v29, s[2:3]
	v_cndmask_b32_e64 v30, v195, v30, s[2:3]
	v_cndmask_b32_e64 v31, v195, v31, s[2:3]
	s_add_i32 s27, s26, 7
	s_cmp_ge_i32 s27, 8
	s_cselect_b64 s[12:13], -1, 0
	s_or_b64 s[12:13], s[12:13], s[36:37]
	v_add_f32_e32 v32, v32, v155
	v_add_f32_e32 v33, v33, v154
	v_add_f32_e32 v34, v34, v153
	v_add_f32_e32 v35, v35, v152
	v_cndmask_b32_e64 v32, v195, v32, s[12:13]
	v_cndmask_b32_e64 v33, v195, v33, s[12:13]
	v_cndmask_b32_e64 v34, v195, v34, s[12:13]
	v_cndmask_b32_e64 v35, v195, v35, s[12:13]
	s_add_i32 s27, s26, 8
	s_cmp_ge_i32 s27, 8
	s_cselect_b64 s[2:3], -1, 0
	s_or_b64 s[2:3], s[2:3], s[36:37]
	s_andn2_b64 s[4:5], s[2:3], s[40:41]
	s_andn2_b64 s[6:7], s[2:3], s[42:43]
	s_andn2_b64 s[8:9], s[2:3], s[44:45]
	s_andn2_b64 s[10:11], s[2:3], s[46:47]
	v_add_f32_e32 v36, v36, v159
	v_add_f32_e32 v37, v37, v158
	v_add_f32_e32 v38, v38, v157
	v_add_f32_e32 v39, v39, v156
	v_cndmask_b32_e64 v36, v195, v36, s[4:5]
	v_cndmask_b32_e64 v37, v195, v37, s[6:7]
	v_cndmask_b32_e64 v38, v195, v38, s[8:9]
	v_cndmask_b32_e64 v39, v195, v39, s[10:11]
	v_max3_f32 v197, v4, v5, v184
	v_max3_f32 v197, v6, v7, v197
	v_max3_f32 v197, v8, v9, v197
	v_max3_f32 v197, v10, v11, v197
	v_max3_f32 v197, v12, v13, v197
	v_max3_f32 v197, v14, v15, v197
	v_max3_f32 v197, v16, v17, v197
	v_max3_f32 v197, v18, v19, v197
	v_max3_f32 v197, v20, v21, v197
	v_max3_f32 v197, v22, v23, v197
	v_max3_f32 v197, v24, v25, v197
	v_max3_f32 v197, v26, v27, v197
	v_max3_f32 v197, v28, v29, v197
	v_max3_f32 v197, v30, v31, v197
	v_max3_f32 v197, v32, v33, v197
	v_max3_f32 v197, v34, v35, v197
	v_max3_f32 v197, v36, v37, v197
	v_max3_f32 v197, v38, v39, v197
	ds_bpermute_b32 v0, v193, v197
	s_waitcnt lgkmcnt(0)
	v_max_f32_e32 v197, v197, v0
	ds_bpermute_b32 v0, v194, v197
	s_waitcnt lgkmcnt(0)
	v_max_f32_e32 v197, v197, v0
	v_sub_f32_e32 v4, v4, v197
	v_sub_f32_e32 v5, v5, v197
	v_sub_f32_e32 v6, v6, v197
	v_sub_f32_e32 v7, v7, v197
	v_sub_f32_e32 v8, v8, v197
	v_sub_f32_e32 v9, v9, v197
	v_sub_f32_e32 v10, v10, v197
	v_sub_f32_e32 v11, v11, v197
	v_sub_f32_e32 v12, v12, v197
	v_sub_f32_e32 v13, v13, v197
	v_sub_f32_e32 v14, v14, v197
	v_sub_f32_e32 v15, v15, v197
	v_sub_f32_e32 v16, v16, v197
	v_sub_f32_e32 v17, v17, v197
	v_sub_f32_e32 v18, v18, v197
	v_sub_f32_e32 v19, v19, v197
	v_sub_f32_e32 v20, v20, v197
	v_sub_f32_e32 v21, v21, v197
	v_sub_f32_e32 v22, v22, v197
	v_sub_f32_e32 v23, v23, v197
	v_sub_f32_e32 v24, v24, v197
	v_sub_f32_e32 v25, v25, v197
	v_sub_f32_e32 v26, v26, v197
	v_sub_f32_e32 v27, v27, v197
	v_sub_f32_e32 v28, v28, v197
	v_sub_f32_e32 v29, v29, v197
	v_sub_f32_e32 v30, v30, v197
	v_sub_f32_e32 v31, v31, v197
	v_sub_f32_e32 v32, v32, v197
	v_sub_f32_e32 v33, v33, v197
	v_sub_f32_e32 v34, v34, v197
	v_sub_f32_e32 v35, v35, v197
	v_sub_f32_e32 v36, v36, v197
	v_sub_f32_e32 v37, v37, v197
	v_sub_f32_e32 v38, v38, v197
	v_sub_f32_e32 v39, v39, v197
	v_sub_f32_e32 v0, v184, v197
	v_exp_f32_e32 v4, v4
	v_exp_f32_e32 v5, v5
	v_exp_f32_e32 v6, v6
	v_exp_f32_e32 v7, v7
	v_exp_f32_e32 v8, v8
	v_exp_f32_e32 v9, v9
	v_exp_f32_e32 v10, v10
	v_exp_f32_e32 v11, v11
	v_exp_f32_e32 v12, v12
	v_exp_f32_e32 v13, v13
	v_exp_f32_e32 v14, v14
	v_exp_f32_e32 v15, v15
	v_exp_f32_e32 v16, v16
	v_exp_f32_e32 v17, v17
	v_exp_f32_e32 v18, v18
	v_exp_f32_e32 v19, v19
	v_exp_f32_e32 v20, v20
	v_exp_f32_e32 v21, v21
	v_exp_f32_e32 v22, v22
	v_exp_f32_e32 v23, v23
	v_exp_f32_e32 v24, v24
	v_exp_f32_e32 v25, v25
	v_exp_f32_e32 v26, v26
	v_exp_f32_e32 v27, v27
	v_exp_f32_e32 v28, v28
	v_exp_f32_e32 v29, v29
	v_exp_f32_e32 v30, v30
	v_exp_f32_e32 v31, v31
	v_exp_f32_e32 v32, v32
	v_exp_f32_e32 v33, v33
	v_exp_f32_e32 v34, v34
	v_exp_f32_e32 v35, v35
	v_exp_f32_e32 v36, v36
	v_exp_f32_e32 v37, v37
	v_exp_f32_e32 v38, v38
	v_exp_f32_e32 v39, v39
	v_exp_f32_e32 v0, v0
	v_pk_add_f32 v[78:79], v[4:5], v[6:7]
	v_pk_add_f32 v[78:79], v[78:79], v[8:9]
	v_pk_add_f32 v[78:79], v[78:79], v[10:11]
	v_pk_add_f32 v[78:79], v[78:79], v[12:13]
	v_pk_add_f32 v[78:79], v[78:79], v[14:15]
	v_pk_add_f32 v[78:79], v[78:79], v[16:17]
	v_pk_add_f32 v[78:79], v[78:79], v[18:19]
	v_pk_add_f32 v[78:79], v[78:79], v[20:21]
	v_pk_add_f32 v[78:79], v[78:79], v[22:23]
	v_pk_add_f32 v[78:79], v[78:79], v[24:25]
	v_pk_add_f32 v[78:79], v[78:79], v[26:27]
	v_pk_add_f32 v[78:79], v[78:79], v[28:29]
	v_pk_add_f32 v[78:79], v[78:79], v[30:31]
	v_pk_add_f32 v[78:79], v[78:79], v[32:33]
	v_pk_add_f32 v[78:79], v[78:79], v[34:35]
	v_pk_add_f32 v[78:79], v[78:79], v[36:37]
	v_pk_add_f32 v[78:79], v[78:79], v[38:39]
	v_add_f32_e32 v1, v78, v79
	ds_bpermute_b32 v3, v193, v1
	s_waitcnt lgkmcnt(0)
	v_add_f32_e32 v1, v1, v3
	ds_bpermute_b32 v3, v194, v1
	s_waitcnt lgkmcnt(0)
	v_add_f32_e32 v1, v1, v3
	v_add_f32_e32 v1, v1, v0
	v_rcp_f32_e32 v198, v1
	v_cvt_pk_bf16_f32 v64, v4, v5
	v_cvt_pk_bf16_f32 v65, v6, v7
	v_cvt_pk_bf16_f32 v66, v8, v9
	v_cvt_pk_bf16_f32 v67, v10, v11
	s_nop 1
	v_mfma_f32_16x16x32_bf16 v[48:51], v[212:215], v[64:67], 0
	v_mfma_f32_16x16x32_bf16 v[52:55], v[216:219], v[64:67], 0
	v_mfma_f32_16x16x32_bf16 v[56:59], v[220:223], v[64:67], 0
	v_mfma_f32_16x16x32_bf16 v[60:63], v[224:227], v[64:67], 0
	ds_read2_b64 v[212:215], v187 offset0:16 offset1:20
	ds_read2_b64 v[216:219], v188 offset0:16 offset1:20
	ds_read2_b64 v[220:223], v189 offset0:16 offset1:20
	ds_read2_b64 v[224:227], v190 offset0:16 offset1:20
	v_cvt_pk_bf16_f32 v68, v12, v13
	v_cvt_pk_bf16_f32 v69, v14, v15
	v_cvt_pk_bf16_f32 v70, v16, v17
	v_cvt_pk_bf16_f32 v71, v18, v19
	s_nop 1
	v_mfma_f32_16x16x32_bf16 v[48:51], v[228:231], v[68:71], v[48:51]
	v_mfma_f32_16x16x32_bf16 v[52:55], v[232:235], v[68:71], v[52:55]
	v_mfma_f32_16x16x32_bf16 v[56:59], v[236:239], v[68:71], v[56:59]
	v_mfma_f32_16x16x32_bf16 v[60:63], v[240:243], v[68:71], v[60:63]
	ds_read2_b64 v[228:231], v187 offset0:24 offset1:28
	ds_read2_b64 v[232:235], v188 offset0:24 offset1:28
	ds_read2_b64 v[236:239], v189 offset0:24 offset1:28
	ds_read2_b64 v[240:243], v190 offset0:24 offset1:28
	v_cvt_pk_bf16_f32 v64, v20, v21
	v_cvt_pk_bf16_f32 v65, v22, v23
	v_cvt_pk_bf16_f32 v66, v24, v25
	v_cvt_pk_bf16_f32 v67, v26, v27
	s_waitcnt lgkmcnt(0)
; __device__ __forceinline__ void ss_add(ss_t* p, float sq) { const float fl = floorf(sq); const unsigned hi = (unsigned)fl, lo = (unsigned)((sq - fl) * 4294967296.0f); atomicAdd(p, ((ss_t)hi << 32) | (ss_t)lo); }
; #define MFMA16(a, b, c) __builtin_amdgcn_mfma_f32_16x16x32_bf16((a), (b), (c), 0, 0, 0)
; template <int PAR> __device__ __forceinline__ void attn_sub(const bf16* KS, const bf16* VT, const float* BTg, const float* gq, float sink2, int n, int ti, int hq, const u32x4 w0, const u32x4 w1, bf16* MIX, ss_t* ssb, int lane) {
;     ...
;         const bf16* kp = KS + (16 * (tb + t) + fr) * KS_STRIDE + 8 * fq;
;         const bf16x8 k0 = *(const bf16x8*)kp, k1 = *(const bf16x8*)(kp + 32);
;         f32x4 acc = (f32x4){0.f, 0.f, 0.f, 0.f};
;         acc = MFMA16(k0, qf[0], acc); acc = MFMA16(k1, qf[1], acc);
;         const bool tv = (n > 0) || (tb + t >= 8);
; #pragma unroll
;         for (int r = 0; r < 4; ++r) { bool valid = tv; if (rel == 0) valid = valid && (e0 + r >= 1); if (rel == 8) valid = valid && (e0 + r <= 0);
;             const float v = valid ? acc[r] + bp[16 * (8 - rel) + (3 - r)] : -1e30f; acc[r] = v; mx = fmaxf(mx, v); }
;     ...
;     for (int p = 0; p < 5; ++p) {
;         u32x4 pw; pw.x = pkbf(sc[2 * p][0], sc[2 * p][1]); pw.y = pkbf(sc[2 * p][2], sc[2 * p][3]); pw.z = pkbf(sc[2 * p + 1][0], sc[2 * p + 1][1]); pw.w = pkbf(sc[2 * p + 1][2], sc[2 * p + 1][3]);
;         const bf16x8 pb = __builtin_bit_cast(bf16x8, pw);
; #pragma unroll
;         for (int dt = 0; dt < 4; ++dt) {
;             const bf16* vp = VT + (16 * dt + fr) * VT_STRIDE + 16 * (tb + 2 * p) + 4 * fq;
;             const u32x2 lo = *(const u32x2*)vp, hi = *(const u32x2*)(vp + 16);
;             const u32x4 va = (u32x4){lo.x, lo.y, hi.x, hi.y};
;             o[dt] = MFMA16(__builtin_bit_cast(bf16x8, va), pb, o[dt]);
;         }
;     }
;     bf16* op = MIX + (size_t)tok * DM + 1024 + hq * 64 + 4 * fq;
;     float sq = 0.f;
; #pragma unroll
;     for (int dt = 0; dt < 4; ++dt) { const f32x4 v = o[dt] * rl; sq += (v[0] * v[0] + v[1] * v[1]) + (v[2] * v[2] + v[3] * v[3]); u32x2 w; w.x = pkbf(v[0], v[1]); w.y = pkbf(v[2], v[3]); *(u32x2*)(op + 16 * dt) = w; }
;     sq += __shfl_xor(sq, 16); sq += __shfl_xor(sq, 32); if (fq == 0) ss_add(ssb + tok, sq);
	s_nop 1
	v_mfma_f32_16x16x32_bf16 v[48:51], v[212:215], v[64:67], v[48:51]
	v_mfma_f32_16x16x32_bf16 v[52:55], v[216:219], v[64:67], v[52:55]
	v_mfma_f32_16x16x32_bf16 v[56:59], v[220:223], v[64:67], v[56:59]
	v_mfma_f32_16x16x32_bf16 v[60:63], v[224:227], v[64:67], v[60:63]
	ds_read_b64 v[212:213], v187 offset:256
	ds_read_b64 v[216:217], v188 offset:256
	ds_read_b64 v[220:221], v189 offset:256
	ds_read_b64 v[224:225], v190 offset:256
	v_cvt_pk_bf16_f32 v68, v28, v29
	v_cvt_pk_bf16_f32 v69, v30, v31
	v_cvt_pk_bf16_f32 v70, v32, v33
	v_cvt_pk_bf16_f32 v71, v34, v35
	s_waitcnt lgkmcnt(0)
	s_nop 1
	v_mfma_f32_16x16x32_bf16 v[48:51], v[228:231], v[68:71], v[48:51]
	v_mfma_f32_16x16x32_bf16 v[52:55], v[232:235], v[68:71], v[52:55]
	v_mfma_f32_16x16x32_bf16 v[56:59], v[236:239], v[68:71], v[56:59]
	v_mfma_f32_16x16x32_bf16 v[60:63], v[240:243], v[68:71], v[60:63]
	v_cvt_pk_bf16_f32 v64, v36, v37
	v_cvt_pk_bf16_f32 v65, v38, v39
	v_mov_b32_e32 v66, 0
	v_mov_b32_e32 v67, 0
	s_waitcnt lgkmcnt(0)
	v_mov_b32_e32 v214, 0
	v_mov_b32_e32 v215, 0
	v_mov_b32_e32 v218, 0
	v_mov_b32_e32 v219, 0
	v_mov_b32_e32 v222, 0
	v_mov_b32_e32 v223, 0
	v_mov_b32_e32 v226, 0
	v_mov_b32_e32 v227, 0
	s_nop 1
	v_mfma_f32_16x16x32_bf16 v[48:51], v[212:215], v[64:67], v[48:51]
	v_mfma_f32_16x16x32_bf16 v[52:55], v[216:219], v[64:67], v[52:55]
	v_mfma_f32_16x16x32_bf16 v[56:59], v[220:223], v[64:67], v[56:59]
	v_mfma_f32_16x16x32_bf16 v[60:63], v[224:227], v[64:67], v[60:63]
	s_nop 7
	s_nop 1
	v_pk_mul_f32 v[48:49], v[198:199], v[48:49] op_sel_hi:[0,1]
	v_pk_mul_f32 v[50:51], v[198:199], v[50:51] op_sel_hi:[0,1]
	v_pk_mul_f32 v[52:53], v[198:199], v[52:53] op_sel_hi:[0,1]
	v_pk_mul_f32 v[54:55], v[198:199], v[54:55] op_sel_hi:[0,1]
	v_pk_mul_f32 v[56:57], v[198:199], v[56:57] op_sel_hi:[0,1]
	v_pk_mul_f32 v[58:59], v[198:199], v[58:59] op_sel_hi:[0,1]
	v_pk_mul_f32 v[60:61], v[198:199], v[60:61] op_sel_hi:[0,1]
	v_pk_mul_f32 v[62:63], v[198:199], v[62:63] op_sel_hi:[0,1]
	v_pk_mul_f32 v[80:81], v[48:49], v[48:49]
	v_pk_fma_f32 v[80:81], v[50:51], v[50:51], v[80:81]
	v_pk_fma_f32 v[80:81], v[52:53], v[52:53], v[80:81]
	v_pk_fma_f32 v[80:81], v[54:55], v[54:55], v[80:81]
	v_pk_fma_f32 v[80:81], v[56:57], v[56:57], v[80:81]
	v_pk_fma_f32 v[80:81], v[58:59], v[58:59], v[80:81]
	v_pk_fma_f32 v[80:81], v[60:61], v[60:61], v[80:81]
	v_pk_fma_f32 v[80:81], v[62:63], v[62:63], v[80:81]
	v_add_f32_e32 v0, v80, v81
	ds_bpermute_b32 v1, v193, v0
	v_cvt_pk_bf16_f32 v48, v48, v49
	v_cvt_pk_bf16_f32 v49, v50, v51
	global_store_dwordx2 v191, v[48:49], s[100:101] offset:0
	v_cvt_pk_bf16_f32 v52, v52, v53
	v_cvt_pk_bf16_f32 v53, v54, v55
	global_store_dwordx2 v191, v[52:53], s[100:101] offset:32
	v_cvt_pk_bf16_f32 v56, v56, v57
	v_cvt_pk_bf16_f32 v57, v58, v59
	global_store_dwordx2 v191, v[56:57], s[100:101] offset:64
	v_cvt_pk_bf16_f32 v60, v60, v61
	v_cvt_pk_bf16_f32 v61, v62, v63
	global_store_dwordx2 v191, v[60:61], s[100:101] offset:96
	s_waitcnt lgkmcnt(0)
	v_add_f32_e32 v0, v0, v1
	ds_bpermute_b32 v1, v194, v0
	s_waitcnt lgkmcnt(0)
	v_add_f32_e32 v0, v0, v1
	s_mov_b64 exec, s[56:57]
	v_floor_f32_e32 v1, v0
	v_sub_f32_e32 v0, v0, v1
	v_mul_f32_e32 v0, 0x4f800000, v0
	v_cvt_u32_f32_e32 v47, v1
	v_cvt_u32_f32_e32 v46, v0
	global_atomic_add_x2 v192, v[46:47], s[100:101] offset:0
	s_mov_b64 exec, -1
	v_add_u32_e32 v191, 0x10000, v191
	ds_read_b128 v[212:215], v185 offset:2304
	ds_read_b128 v[216:219], v185 offset:2368
	ds_read_b128 v[220:223], v185 offset:4608
	ds_read_b128 v[224:227], v185 offset:4672
	ds_read_b128 v[228:231], v185 offset:6912
	ds_read_b128 v[232:235], v185 offset:6976
	ds_read_b128 v[48:51], v185 offset:9216
	ds_read_b128 v[52:55], v185 offset:9280
	ds_read_b128 v[56:59], v185 offset:11520
	ds_read_b128 v[60:63], v185 offset:11584
	ds_read_b128 v[64:67], v185 offset:13824
	ds_read_b128 v[68:71], v185 offset:13888
	s_waitcnt lgkmcnt(6)
	v_mfma_f32_16x16x32_bf16 v[4:7], v[212:215], v[124:127], 0
	v_mfma_f32_16x16x32_bf16 v[8:11], v[220:223], v[124:127], 0
	v_mfma_f32_16x16x32_bf16 v[12:15], v[228:231], v[124:127], 0
	v_mfma_f32_16x16x32_bf16 v[4:7], v[216:219], v[128:131], v[4:7]
	v_mfma_f32_16x16x32_bf16 v[8:11], v[224:227], v[128:131], v[8:11]
	v_mfma_f32_16x16x32_bf16 v[12:15], v[232:235], v[128:131], v[12:15]
	ds_read_b128 v[212:215], v185 offset:16128
	ds_read_b128 v[216:219], v185 offset:16192
	ds_read_b128 v[220:223], v185 offset:18432
	ds_read_b128 v[224:227], v185 offset:18496
	ds_read_b128 v[228:231], v185 offset:20736
	ds_read_b128 v[232:235], v185 offset:20800
	s_waitcnt lgkmcnt(6)
	v_mfma_f32_16x16x32_bf16 v[16:19], v[48:51], v[124:127], 0
	v_mfma_f32_16x16x32_bf16 v[20:23], v[56:59], v[124:127], 0
	v_mfma_f32_16x16x32_bf16 v[24:27], v[64:67], v[124:127], 0
	v_mfma_f32_16x16x32_bf16 v[16:19], v[52:55], v[128:131], v[16:19]
	v_mfma_f32_16x16x32_bf16 v[20:23], v[60:63], v[128:131], v[20:23]
	v_mfma_f32_16x16x32_bf16 v[24:27], v[68:71], v[128:131], v[24:27]
	s_add_i32 s27, s26, 1
	s_cmp_ge_i32 s27, 8
	s_cselect_b64 s[2:3], -1, 0
	s_or_b64 s[2:3], s[2:3], s[36:37]
	s_and_b64 s[4:5], s[2:3], s[40:41]
	s_and_b64 s[6:7], s[2:3], s[42:43]
	s_and_b64 s[8:9], s[2:3], s[44:45]
	s_and_b64 s[10:11], s[2:3], s[46:47]
	v_add_f32_e32 v4, v4, v87
	v_add_f32_e32 v5, v5, v86
	v_add_f32_e32 v6, v6, v85
	v_add_f32_e32 v7, v7, v84
	v_cndmask_b32_e64 v4, v195, v4, s[4:5]
	v_cndmask_b32_e64 v5, v195, v5, s[6:7]
	v_cndmask_b32_e64 v6, v195, v6, s[8:9]
	v_cndmask_b32_e64 v7, v195, v7, s[10:11]
	s_add_i32 s27, s26, 2
	s_cmp_ge_i32 s27, 8
	s_cselect_b64 s[12:13], -1, 0
	s_or_b64 s[12:13], s[12:13], s[36:37]
	v_add_f32_e32 v8, v8, v91
	v_add_f32_e32 v9, v9, v90
	v_add_f32_e32 v10, v10, v89
	v_add_f32_e32 v11, v11, v88
	v_cndmask_b32_e64 v8, v195, v8, s[12:13]
	v_cndmask_b32_e64 v9, v195, v9, s[12:13]
	v_cndmask_b32_e64 v10, v195, v10, s[12:13]
	v_cndmask_b32_e64 v11, v195, v11, s[12:13]
	s_add_i32 s27, s26, 3
	s_cmp_ge_i32 s27, 8
	s_cselect_b64 s[2:3], -1, 0
	s_or_b64 s[2:3], s[2:3], s[36:37]
	v_add_f32_e32 v12, v12, v95
	v_add_f32_e32 v13, v13, v94
	v_add_f32_e32 v14, v14, v93
	v_add_f32_e32 v15, v15, v92
	v_cndmask_b32_e64 v12, v195, v12, s[2:3]
	v_cndmask_b32_e64 v13, v195, v13, s[2:3]
	v_cndmask_b32_e64 v14, v195, v14, s[2:3]
	v_cndmask_b32_e64 v15, v195, v15, s[2:3]
	s_waitcnt lgkmcnt(0)
; #define MFMA16(a, b, c) __builtin_amdgcn_mfma_f32_16x16x32_bf16((a), (b), (c), 0, 0, 0)
; template <int PAR> __device__ __forceinline__ void attn_sub(const bf16* KS, const bf16* VT, const float* BTg, const float* gq, float sink2, int n, int ti, int hq, const u32x4 w0, const u32x4 w1, bf16* MIX, ss_t* ssb, int lane) {
;     ...
;     for (int t = 0; t < 10; ++t) {
;         constexpr int dummy = 0; (void)dummy;
;         const int rel = t - PAR;
;         if (rel < 0 || rel > 8) { sc[t] = (f32x4){0.f, 0.f, 0.f, 0.f}; continue; }
;         const bf16* kp = KS + (16 * (tb + t) + fr) * KS_STRIDE + 8 * fq;
;         const bf16x8 k0 = *(const bf16x8*)kp, k1 = *(const bf16x8*)(kp + 32);
;         f32x4 acc = (f32x4){0.f, 0.f, 0.f, 0.f};
;         acc = MFMA16(k0, qf[0], acc); acc = MFMA16(k1, qf[1], acc);
;         const bool tv = (n > 0) || (tb + t >= 8);
; #pragma unroll
;         for (int r = 0; r < 4; ++r) { bool valid = tv; if (rel == 0) valid = valid && (e0 + r >= 1); if (rel == 8) valid = valid && (e0 + r <= 0);
;             const float v = valid ? acc[r] + bp[16 * (8 - rel) + (3 - r)] : -1e30f; acc[r] = v; mx = fmaxf(mx, v); }
;         sc[t] = acc;
;     }
;     mx = fmaxf(mx, __shfl_xor(mx, 16)); mx = fmaxf(mx, __shfl_xor(mx, 32));
;     float lsum = 0.f;
; #pragma unroll
;     for (int t = 0; t < 10; ++t) { const int rel = t - PAR; if (rel < 0 || rel > 8) continue;
; #pragma unroll
;         for (int r = 0; r < 4; ++r) { const float p = __builtin_amdgcn_exp2f(sc[t][r] - mx); sc[t][r] = p; lsum += p; } }
	v_mfma_f32_16x16x32_bf16 v[28:31], v[212:215], v[124:127], 0
	v_mfma_f32_16x16x32_bf16 v[32:35], v[220:223], v[124:127], 0
	v_mfma_f32_16x16x32_bf16 v[36:39], v[228:231], v[124:127], 0
	v_mfma_f32_16x16x32_bf16 v[28:31], v[216:219], v[128:131], v[28:31]
	v_mfma_f32_16x16x32_bf16 v[32:35], v[224:227], v[128:131], v[32:35]
	v_mfma_f32_16x16x32_bf16 v[36:39], v[232:235], v[128:131], v[36:39]
	ds_read2_b64 v[212:215], v187 offset0:4 offset1:8
	ds_read2_b64 v[216:219], v188 offset0:4 offset1:8
	ds_read2_b64 v[220:223], v189 offset0:4 offset1:8
	ds_read2_b64 v[224:227], v190 offset0:4 offset1:8
	ds_read2_b64 v[228:231], v187 offset0:12 offset1:16
	ds_read2_b64 v[232:235], v188 offset0:12 offset1:16
	ds_read2_b64 v[236:239], v189 offset0:12 offset1:16
	ds_read2_b64 v[240:243], v190 offset0:12 offset1:16
	s_add_i32 s27, s26, 4
	s_cmp_ge_i32 s27, 8
	s_cselect_b64 s[12:13], -1, 0
	s_or_b64 s[12:13], s[12:13], s[36:37]
	v_add_f32_e32 v16, v16, v99
	v_add_f32_e32 v17, v17, v98
	v_add_f32_e32 v18, v18, v97
	v_add_f32_e32 v19, v19, v96
	v_cndmask_b32_e64 v16, v195, v16, s[12:13]
	v_cndmask_b32_e64 v17, v195, v17, s[12:13]
	v_cndmask_b32_e64 v18, v195, v18, s[12:13]
	v_cndmask_b32_e64 v19, v195, v19, s[12:13]
	s_add_i32 s27, s26, 5
	s_cmp_ge_i32 s27, 8
	s_cselect_b64 s[2:3], -1, 0
	s_or_b64 s[2:3], s[2:3], s[36:37]
	v_add_f32_e32 v20, v20, v43
	v_add_f32_e32 v21, v21, v42
	v_add_f32_e32 v22, v22, v41
	v_add_f32_e32 v23, v23, v40
	v_cndmask_b32_e64 v20, v195, v20, s[2:3]
	v_cndmask_b32_e64 v21, v195, v21, s[2:3]
	v_cndmask_b32_e64 v22, v195, v22, s[2:3]
	v_cndmask_b32_e64 v23, v195, v23, s[2:3]
	s_add_i32 s27, s26, 6
	s_cmp_ge_i32 s27, 8
	s_cselect_b64 s[12:13], -1, 0
	s_or_b64 s[12:13], s[12:13], s[36:37]
	v_add_f32_e32 v24, v24, v75
	v_add_f32_e32 v25, v25, v74
	v_add_f32_e32 v26, v26, v73
	v_add_f32_e32 v27, v27, v72
	v_cndmask_b32_e64 v24, v195, v24, s[12:13]
	v_cndmask_b32_e64 v25, v195, v25, s[12:13]
	v_cndmask_b32_e64 v26, v195, v26, s[12:13]
	v_cndmask_b32_e64 v27, v195, v27, s[12:13]
	s_add_i32 s27, s26, 7
	s_cmp_ge_i32 s27, 8
	s_cselect_b64 s[2:3], -1, 0
	s_or_b64 s[2:3], s[2:3], s[36:37]
	v_add_f32_e32 v28, v28, v151
	v_add_f32_e32 v29, v29, v150
	v_add_f32_e32 v30, v30, v149
	v_add_f32_e32 v31, v31, v148
	v_cndmask_b32_e64 v28, v195, v28, s[2:3]
	v_cndmask_b32_e64 v29, v195, v29, s[2:3]
	v_cndmask_b32_e64 v30, v195, v30, s[2:3]
	v_cndmask_b32_e64 v31, v195, v31, s[2:3]
	s_add_i32 s27, s26, 8
	s_cmp_ge_i32 s27, 8
	s_cselect_b64 s[12:13], -1, 0
	s_or_b64 s[12:13], s[12:13], s[36:37]
	v_add_f32_e32 v32, v32, v155
	v_add_f32_e32 v33, v33, v154
	v_add_f32_e32 v34, v34, v153
	v_add_f32_e32 v35, v35, v152
	v_cndmask_b32_e64 v32, v195, v32, s[12:13]
	v_cndmask_b32_e64 v33, v195, v33, s[12:13]
	v_cndmask_b32_e64 v34, v195, v34, s[12:13]
	v_cndmask_b32_e64 v35, v195, v35, s[12:13]
	s_add_i32 s27, s26, 9
	s_cmp_ge_i32 s27, 8
	s_cselect_b64 s[2:3], -1, 0
	s_or_b64 s[2:3], s[2:3], s[36:37]
	s_andn2_b64 s[4:5], s[2:3], s[40:41]
	s_andn2_b64 s[6:7], s[2:3], s[42:43]
	s_andn2_b64 s[8:9], s[2:3], s[44:45]
	s_andn2_b64 s[10:11], s[2:3], s[46:47]
	v_add_f32_e32 v36, v36, v159
	v_add_f32_e32 v37, v37, v158
	v_add_f32_e32 v38, v38, v157
	v_add_f32_e32 v39, v39, v156
	v_cndmask_b32_e64 v36, v195, v36, s[4:5]
	v_cndmask_b32_e64 v37, v195, v37, s[6:7]
	v_cndmask_b32_e64 v38, v195, v38, s[8:9]
	v_cndmask_b32_e64 v39, v195, v39, s[10:11]
	v_max3_f32 v197, v4, v5, v184
	v_max3_f32 v197, v6, v7, v197
	v_max3_f32 v197, v8, v9, v197
	v_max3_f32 v197, v10, v11, v197
	v_max3_f32 v197, v12, v13, v197
	v_max3_f32 v197, v14, v15, v197
	v_max3_f32 v197, v16, v17, v197
	v_max3_f32 v197, v18, v19, v197
	v_max3_f32 v197, v20, v21, v197
	v_max3_f32 v197, v22, v23, v197
	v_max3_f32 v197, v24, v25, v197
	v_max3_f32 v197, v26, v27, v197
	v_max3_f32 v197, v28, v29, v197
	v_max3_f32 v197, v30, v31, v197
	v_max3_f32 v197, v32, v33, v197
	v_max3_f32 v197, v34, v35, v197
	v_max3_f32 v197, v36, v37, v197
	v_max3_f32 v197, v38, v39, v197
	ds_bpermute_b32 v0, v193, v197
	s_waitcnt lgkmcnt(0)
	v_max_f32_e32 v197, v197, v0
	ds_bpermute_b32 v0, v194, v197
	s_waitcnt lgkmcnt(0)
	v_max_f32_e32 v197, v197, v0
	v_sub_f32_e32 v4, v4, v197
	v_sub_f32_e32 v5, v5, v197
	v_sub_f32_e32 v6, v6, v197
	v_sub_f32_e32 v7, v7, v197
	v_sub_f32_e32 v8, v8, v197
	v_sub_f32_e32 v9, v9, v197
	v_sub_f32_e32 v10, v10, v197
	v_sub_f32_e32 v11, v11, v197
	v_sub_f32_e32 v12, v12, v197
	v_sub_f32_e32 v13, v13, v197
	v_sub_f32_e32 v14, v14, v197
	v_sub_f32_e32 v15, v15, v197
	v_sub_f32_e32 v16, v16, v197
	v_sub_f32_e32 v17, v17, v197
	v_sub_f32_e32 v18, v18, v197
	v_sub_f32_e32 v19, v19, v197
	v_sub_f32_e32 v20, v20, v197
	v_sub_f32_e32 v21, v21, v197
	v_sub_f32_e32 v22, v22, v197
	v_sub_f32_e32 v23, v23, v197
	v_sub_f32_e32 v24, v24, v197
	v_sub_f32_e32 v25, v25, v197
	v_sub_f32_e32 v26, v26, v197
	v_sub_f32_e32 v27, v27, v197
	v_sub_f32_e32 v28, v28, v197
	v_sub_f32_e32 v29, v29, v197
	v_sub_f32_e32 v30, v30, v197
	v_sub_f32_e32 v31, v31, v197
	v_sub_f32_e32 v32, v32, v197
	v_sub_f32_e32 v33, v33, v197
	v_sub_f32_e32 v34, v34, v197
	v_sub_f32_e32 v35, v35, v197
	v_sub_f32_e32 v36, v36, v197
	v_sub_f32_e32 v37, v37, v197
	v_sub_f32_e32 v38, v38, v197
	v_sub_f32_e32 v39, v39, v197
	v_sub_f32_e32 v0, v184, v197
	v_exp_f32_e32 v4, v4
	v_exp_f32_e32 v5, v5
	v_exp_f32_e32 v6, v6
	v_exp_f32_e32 v7, v7
	v_exp_f32_e32 v8, v8
	v_exp_f32_e32 v9, v9
	v_exp_f32_e32 v10, v10
	v_exp_f32_e32 v11, v11
	v_exp_f32_e32 v12, v12
	v_exp_f32_e32 v13, v13
	v_exp_f32_e32 v14, v14
	v_exp_f32_e32 v15, v15
	v_exp_f32_e32 v16, v16
	v_exp_f32_e32 v17, v17
	v_exp_f32_e32 v18, v18
	v_exp_f32_e32 v19, v19
	v_exp_f32_e32 v20, v20
	v_exp_f32_e32 v21, v21
	v_exp_f32_e32 v22, v22
	v_exp_f32_e32 v23, v23
	v_exp_f32_e32 v24, v24
	v_exp_f32_e32 v25, v25
	v_exp_f32_e32 v26, v26
	v_exp_f32_e32 v27, v27
	v_exp_f32_e32 v28, v28
	v_exp_f32_e32 v29, v29
	v_exp_f32_e32 v30, v30
	v_exp_f32_e32 v31, v31
	v_exp_f32_e32 v32, v32
	v_exp_f32_e32 v33, v33
	v_exp_f32_e32 v34, v34
	v_exp_f32_e32 v35, v35
	v_exp_f32_e32 v36, v36
	v_exp_f32_e32 v37, v37
	v_exp_f32_e32 v38, v38
	v_exp_f32_e32 v39, v39
	v_exp_f32_e32 v0, v0
	v_pk_add_f32 v[78:79], v[4:5], v[6:7]
	v_pk_add_f32 v[78:79], v[78:79], v[8:9]
	v_pk_add_f32 v[78:79], v[78:79], v[10:11]
	v_pk_add_f32 v[78:79], v[78:79], v[12:13]
	v_pk_add_f32 v[78:79], v[78:79], v[14:15]
	v_pk_add_f32 v[78:79], v[78:79], v[16:17]
	v_pk_add_f32 v[78:79], v[78:79], v[18:19]
	v_pk_add_f32 v[78:79], v[78:79], v[20:21]
	v_pk_add_f32 v[78:79], v[78:79], v[22:23]
	v_pk_add_f32 v[78:79], v[78:79], v[24:25]
	v_pk_add_f32 v[78:79], v[78:79], v[26:27]
	v_pk_add_f32 v[78:79], v[78:79], v[28:29]
	v_pk_add_f32 v[78:79], v[78:79], v[30:31]
	v_pk_add_f32 v[78:79], v[78:79], v[32:33]
	v_pk_add_f32 v[78:79], v[78:79], v[34:35]
	v_pk_add_f32 v[78:79], v[78:79], v[36:37]
	v_pk_add_f32 v[78:79], v[78:79], v[38:39]
	v_add_f32_e32 v1, v78, v79
	ds_bpermute_b32 v3, v193, v1
	s_waitcnt lgkmcnt(0)
; __device__ __forceinline__ void ss_add(ss_t* p, float sq) { const float fl = floorf(sq); const unsigned hi = (unsigned)fl, lo = (unsigned)((sq - fl) * 4294967296.0f); atomicAdd(p, ((ss_t)hi << 32) | (ss_t)lo); }
; __device__ __forceinline__ unsigned pkbf(float lo, float hi) { typedef float f2_t __attribute__((ext_vector_type(2))); typedef __bf16 b2_t __attribute__((ext_vector_type(2))); f2_t v = {lo, hi}; b2_t b = __builtin_convertvector(v, b2_t); return __builtin_bit_cast(unsigned, b); }
; #define MFMA16(a, b, c) __builtin_amdgcn_mfma_f32_16x16x32_bf16((a), (b), (c), 0, 0, 0)
; template <int PAR> __device__ __forceinline__ void attn_sub(const bf16* KS, const bf16* VT, const float* BTg, const float* gq, float sink2, int n, int ti, int hq, const u32x4 w0, const u32x4 w1, bf16* MIX, ss_t* ssb, int lane) {
;     ...
;     lsum += __shfl_xor(lsum, 16); lsum += __shfl_xor(lsum, 32);
;     lsum += __builtin_amdgcn_exp2f(sink2 - mx);
;     const float rl = 1.0f / lsum;
;     f32x4 o[4];
; #pragma unroll
;     for (int dt = 0; dt < 4; ++dt) o[dt] = (f32x4){0.f, 0.f, 0.f, 0.f};
; #pragma unroll
;     for (int p = 0; p < 5; ++p) {
;         u32x4 pw; pw.x = pkbf(sc[2 * p][0], sc[2 * p][1]); pw.y = pkbf(sc[2 * p][2], sc[2 * p][3]); pw.z = pkbf(sc[2 * p + 1][0], sc[2 * p + 1][1]); pw.w = pkbf(sc[2 * p + 1][2], sc[2 * p + 1][3]);
;         const bf16x8 pb = __builtin_bit_cast(bf16x8, pw);
; #pragma unroll
;         for (int dt = 0; dt < 4; ++dt) {
;             const bf16* vp = VT + (16 * dt + fr) * VT_STRIDE + 16 * (tb + 2 * p) + 4 * fq;
;             const u32x2 lo = *(const u32x2*)vp, hi = *(const u32x2*)(vp + 16);
;             const u32x4 va = (u32x4){lo.x, lo.y, hi.x, hi.y};
;             o[dt] = MFMA16(__builtin_bit_cast(bf16x8, va), pb, o[dt]);
;         }
;     }
;     bf16* op = MIX + (size_t)tok * DM + 1024 + hq * 64 + 4 * fq;
;     float sq = 0.f;
; #pragma unroll
;     for (int dt = 0; dt < 4; ++dt) { const f32x4 v = o[dt] * rl; sq += (v[0] * v[0] + v[1] * v[1]) + (v[2] * v[2] + v[3] * v[3]); u32x2 w; w.x = pkbf(v[0], v[1]); w.y = pkbf(v[2], v[3]); *(u32x2*)(op + 16 * dt) = w; }
;     sq += __shfl_xor(sq, 16); sq += __shfl_xor(sq, 32); if (fq == 0) ss_add(ssb + tok, sq);
	v_add_f32_e32 v1, v1, v3
	ds_bpermute_b32 v3, v194, v1
	s_waitcnt lgkmcnt(0)
	v_add_f32_e32 v1, v1, v3
	v_add_f32_e32 v1, v1, v0
	v_rcp_f32_e32 v198, v1
	v_cvt_pk_bf16_f32 v64, v4, v5
	v_cvt_pk_bf16_f32 v65, v6, v7
	v_cvt_pk_bf16_f32 v66, v8, v9
	v_cvt_pk_bf16_f32 v67, v10, v11
	s_nop 1
	v_mfma_f32_16x16x32_bf16 v[48:51], v[212:215], v[64:67], 0
	v_mfma_f32_16x16x32_bf16 v[52:55], v[216:219], v[64:67], 0
	v_mfma_f32_16x16x32_bf16 v[56:59], v[220:223], v[64:67], 0
	v_mfma_f32_16x16x32_bf16 v[60:63], v[224:227], v[64:67], 0
	ds_read2_b64 v[212:215], v187 offset0:20 offset1:24
	ds_read2_b64 v[216:219], v188 offset0:20 offset1:24
	ds_read2_b64 v[220:223], v189 offset0:20 offset1:24
	ds_read2_b64 v[224:227], v190 offset0:20 offset1:24
	v_cvt_pk_bf16_f32 v68, v12, v13
	v_cvt_pk_bf16_f32 v69, v14, v15
	v_cvt_pk_bf16_f32 v70, v16, v17
	v_cvt_pk_bf16_f32 v71, v18, v19
	s_nop 1
	v_mfma_f32_16x16x32_bf16 v[48:51], v[228:231], v[68:71], v[48:51]
	v_mfma_f32_16x16x32_bf16 v[52:55], v[232:235], v[68:71], v[52:55]
	v_mfma_f32_16x16x32_bf16 v[56:59], v[236:239], v[68:71], v[56:59]
	v_mfma_f32_16x16x32_bf16 v[60:63], v[240:243], v[68:71], v[60:63]
	ds_read2_b64 v[228:231], v187 offset0:28 offset1:32
	ds_read2_b64 v[232:235], v188 offset0:28 offset1:32
	ds_read2_b64 v[236:239], v189 offset0:28 offset1:32
	ds_read2_b64 v[240:243], v190 offset0:28 offset1:32
	v_cvt_pk_bf16_f32 v64, v20, v21
	v_cvt_pk_bf16_f32 v65, v22, v23
	v_cvt_pk_bf16_f32 v66, v24, v25
	v_cvt_pk_bf16_f32 v67, v26, v27
	s_waitcnt lgkmcnt(0)
	s_nop 1
	v_mfma_f32_16x16x32_bf16 v[48:51], v[212:215], v[64:67], v[48:51]
	v_mfma_f32_16x16x32_bf16 v[52:55], v[216:219], v[64:67], v[52:55]
	v_mfma_f32_16x16x32_bf16 v[56:59], v[220:223], v[64:67], v[56:59]
	v_mfma_f32_16x16x32_bf16 v[60:63], v[224:227], v[64:67], v[60:63]
	ds_read_b64 v[212:213], v187 offset:288
	ds_read_b64 v[216:217], v188 offset:288
	ds_read_b64 v[220:221], v189 offset:288
	ds_read_b64 v[224:225], v190 offset:288
	v_cvt_pk_bf16_f32 v68, v28, v29
	v_cvt_pk_bf16_f32 v69, v30, v31
	v_cvt_pk_bf16_f32 v70, v32, v33
	v_cvt_pk_bf16_f32 v71, v34, v35
	s_waitcnt lgkmcnt(0)
	s_nop 1
	v_mfma_f32_16x16x32_bf16 v[48:51], v[228:231], v[68:71], v[48:51]
	v_mfma_f32_16x16x32_bf16 v[52:55], v[232:235], v[68:71], v[52:55]
	v_mfma_f32_16x16x32_bf16 v[56:59], v[236:239], v[68:71], v[56:59]
	v_mfma_f32_16x16x32_bf16 v[60:63], v[240:243], v[68:71], v[60:63]
	v_cvt_pk_bf16_f32 v64, v36, v37
	v_cvt_pk_bf16_f32 v65, v38, v39
	v_mov_b32_e32 v66, 0
	v_mov_b32_e32 v67, 0
	s_waitcnt lgkmcnt(0)
	v_mov_b32_e32 v214, 0
	v_mov_b32_e32 v215, 0
	v_mov_b32_e32 v218, 0
	v_mov_b32_e32 v219, 0
	v_mov_b32_e32 v222, 0
	v_mov_b32_e32 v223, 0
	v_mov_b32_e32 v226, 0
	v_mov_b32_e32 v227, 0
	s_nop 1
	v_mfma_f32_16x16x32_bf16 v[48:51], v[212:215], v[64:67], v[48:51]
	v_mfma_f32_16x16x32_bf16 v[52:55], v[216:219], v[64:67], v[52:55]
	v_mfma_f32_16x16x32_bf16 v[56:59], v[220:223], v[64:67], v[56:59]
	v_mfma_f32_16x16x32_bf16 v[60:63], v[224:227], v[64:67], v[60:63]
	s_nop 7
	s_nop 1
	v_pk_mul_f32 v[48:49], v[198:199], v[48:49] op_sel_hi:[0,1]
	v_pk_mul_f32 v[50:51], v[198:199], v[50:51] op_sel_hi:[0,1]
	v_pk_mul_f32 v[52:53], v[198:199], v[52:53] op_sel_hi:[0,1]
	v_pk_mul_f32 v[54:55], v[198:199], v[54:55] op_sel_hi:[0,1]
	v_pk_mul_f32 v[56:57], v[198:199], v[56:57] op_sel_hi:[0,1]
	v_pk_mul_f32 v[58:59], v[198:199], v[58:59] op_sel_hi:[0,1]
	v_pk_mul_f32 v[60:61], v[198:199], v[60:61] op_sel_hi:[0,1]
	v_pk_mul_f32 v[62:63], v[198:199], v[62:63] op_sel_hi:[0,1]
	v_pk_mul_f32 v[80:81], v[48:49], v[48:49]
	v_pk_fma_f32 v[80:81], v[50:51], v[50:51], v[80:81]
	v_pk_fma_f32 v[80:81], v[52:53], v[52:53], v[80:81]
	v_pk_fma_f32 v[80:81], v[54:55], v[54:55], v[80:81]
	v_pk_fma_f32 v[80:81], v[56:57], v[56:57], v[80:81]
	v_pk_fma_f32 v[80:81], v[58:59], v[58:59], v[80:81]
	v_pk_fma_f32 v[80:81], v[60:61], v[60:61], v[80:81]
	v_pk_fma_f32 v[80:81], v[62:63], v[62:63], v[80:81]
	v_add_f32_e32 v0, v80, v81
	ds_bpermute_b32 v1, v193, v0
	v_cvt_pk_bf16_f32 v48, v48, v49
	v_cvt_pk_bf16_f32 v49, v50, v51
	global_store_dwordx2 v191, v[48:49], s[100:101] offset:0
	v_cvt_pk_bf16_f32 v52, v52, v53
	v_cvt_pk_bf16_f32 v53, v54, v55
	global_store_dwordx2 v191, v[52:53], s[100:101] offset:32
	v_cvt_pk_bf16_f32 v56, v56, v57
	v_cvt_pk_bf16_f32 v57, v58, v59
	global_store_dwordx2 v191, v[56:57], s[100:101] offset:64
	v_cvt_pk_bf16_f32 v60, v60, v61
	v_cvt_pk_bf16_f32 v61, v62, v63
	global_store_dwordx2 v191, v[60:61], s[100:101] offset:96
	s_waitcnt lgkmcnt(0)
	v_add_f32_e32 v0, v0, v1
	ds_bpermute_b32 v1, v194, v0
	s_waitcnt lgkmcnt(0)
	v_add_f32_e32 v0, v0, v1
	s_mov_b64 exec, s[56:57]
	v_floor_f32_e32 v1, v0
	v_sub_f32_e32 v0, v0, v1
	v_mul_f32_e32 v0, 0x4f800000, v0
	v_cvt_u32_f32_e32 v47, v1
	v_cvt_u32_f32_e32 v46, v0
	global_atomic_add_x2 v192, v[46:47], s[100:101] offset:128
	s_mov_b64 exec, -1
	v_add_u32_e32 v191, 0x10000, v191
	ds_read_b128 v[212:215], v185 offset:4608
	ds_read_b128 v[216:219], v185 offset:4672
	ds_read_b128 v[220:223], v185 offset:6912
	ds_read_b128 v[224:227], v185 offset:6976
	ds_read_b128 v[228:231], v185 offset:9216
	ds_read_b128 v[232:235], v185 offset:9280
	ds_read_b128 v[48:51], v185 offset:11520
	ds_read_b128 v[52:55], v185 offset:11584
	ds_read_b128 v[56:59], v185 offset:13824
	ds_read_b128 v[60:63], v185 offset:13888
	ds_read_b128 v[64:67], v185 offset:16128
	ds_read_b128 v[68:71], v185 offset:16192
	s_waitcnt lgkmcnt(6)
; #define MFMA16(a, b, c) __builtin_amdgcn_mfma_f32_16x16x32_bf16((a), (b), (c), 0, 0, 0)
; template <int PAR> __device__ __forceinline__ void attn_sub(const bf16* KS, const bf16* VT, const float* BTg, const float* gq, float sink2, int n, int ti, int hq, const u32x4 w0, const u32x4 w1, bf16* MIX, ss_t* ssb, int lane) {
;     ...
;     for (int t = 0; t < 10; ++t) {
;         constexpr int dummy = 0; (void)dummy;
;         const int rel = t - PAR;
;         if (rel < 0 || rel > 8) { sc[t] = (f32x4){0.f, 0.f, 0.f, 0.f}; continue; }
;         const bf16* kp = KS + (16 * (tb + t) + fr) * KS_STRIDE + 8 * fq;
;         const bf16x8 k0 = *(const bf16x8*)kp, k1 = *(const bf16x8*)(kp + 32);
;         f32x4 acc = (f32x4){0.f, 0.f, 0.f, 0.f};
;         acc = MFMA16(k0, qf[0], acc); acc = MFMA16(k1, qf[1], acc);
;         const bool tv = (n > 0) || (tb + t >= 8);
; #pragma unroll
;         for (int r = 0; r < 4; ++r) { bool valid = tv; if (rel == 0) valid = valid && (e0 + r >= 1); if (rel == 8) valid = valid && (e0 + r <= 0);
;             const float v = valid ? acc[r] + bp[16 * (8 - rel) + (3 - r)] : -1e30f; acc[r] = v; mx = fmaxf(mx, v); }
;         sc[t] = acc;
;     }
;     mx = fmaxf(mx, __shfl_xor(mx, 16)); mx = fmaxf(mx, __shfl_xor(mx, 32));
	v_mfma_f32_16x16x32_bf16 v[4:7], v[212:215], v[132:135], 0
	v_mfma_f32_16x16x32_bf16 v[8:11], v[220:223], v[132:135], 0
	v_mfma_f32_16x16x32_bf16 v[12:15], v[228:231], v[132:135], 0
	v_mfma_f32_16x16x32_bf16 v[4:7], v[216:219], v[136:139], v[4:7]
	v_mfma_f32_16x16x32_bf16 v[8:11], v[224:227], v[136:139], v[8:11]
	v_mfma_f32_16x16x32_bf16 v[12:15], v[232:235], v[136:139], v[12:15]
	ds_read_b128 v[212:215], v185 offset:18432
	ds_read_b128 v[216:219], v185 offset:18496
	ds_read_b128 v[220:223], v185 offset:20736
	ds_read_b128 v[224:227], v185 offset:20800
	ds_read_b128 v[228:231], v185 offset:23040
	ds_read_b128 v[232:235], v185 offset:23104
	s_waitcnt lgkmcnt(6)
	v_mfma_f32_16x16x32_bf16 v[16:19], v[48:51], v[132:135], 0
	v_mfma_f32_16x16x32_bf16 v[20:23], v[56:59], v[132:135], 0
	v_mfma_f32_16x16x32_bf16 v[24:27], v[64:67], v[132:135], 0
	v_mfma_f32_16x16x32_bf16 v[16:19], v[52:55], v[136:139], v[16:19]
	v_mfma_f32_16x16x32_bf16 v[20:23], v[60:63], v[136:139], v[20:23]
	v_mfma_f32_16x16x32_bf16 v[24:27], v[68:71], v[136:139], v[24:27]
	s_add_i32 s27, s26, 2
	s_cmp_ge_i32 s27, 8
	s_cselect_b64 s[2:3], -1, 0
	s_or_b64 s[2:3], s[2:3], s[36:37]
	s_and_b64 s[4:5], s[2:3], s[40:41]
	s_and_b64 s[6:7], s[2:3], s[42:43]
	s_and_b64 s[8:9], s[2:3], s[44:45]
	s_and_b64 s[10:11], s[2:3], s[46:47]
	v_add_f32_e32 v4, v4, v87
	v_add_f32_e32 v5, v5, v86
	v_add_f32_e32 v6, v6, v85
	v_add_f32_e32 v7, v7, v84
	v_cndmask_b32_e64 v4, v195, v4, s[4:5]
	v_cndmask_b32_e64 v5, v195, v5, s[6:7]
	v_cndmask_b32_e64 v6, v195, v6, s[8:9]
	v_cndmask_b32_e64 v7, v195, v7, s[10:11]
	s_add_i32 s27, s26, 3
	s_cmp_ge_i32 s27, 8
	s_cselect_b64 s[12:13], -1, 0
	s_or_b64 s[12:13], s[12:13], s[36:37]
	v_add_f32_e32 v8, v8, v91
	v_add_f32_e32 v9, v9, v90
	v_add_f32_e32 v10, v10, v89
	v_add_f32_e32 v11, v11, v88
	v_cndmask_b32_e64 v8, v195, v8, s[12:13]
	v_cndmask_b32_e64 v9, v195, v9, s[12:13]
	v_cndmask_b32_e64 v10, v195, v10, s[12:13]
	v_cndmask_b32_e64 v11, v195, v11, s[12:13]
	s_add_i32 s27, s26, 4
	s_cmp_ge_i32 s27, 8
	s_cselect_b64 s[2:3], -1, 0
	s_or_b64 s[2:3], s[2:3], s[36:37]
	v_add_f32_e32 v12, v12, v95
	v_add_f32_e32 v13, v13, v94
	v_add_f32_e32 v14, v14, v93
	v_add_f32_e32 v15, v15, v92
	v_cndmask_b32_e64 v12, v195, v12, s[2:3]
	v_cndmask_b32_e64 v13, v195, v13, s[2:3]
	v_cndmask_b32_e64 v14, v195, v14, s[2:3]
	v_cndmask_b32_e64 v15, v195, v15, s[2:3]
	s_waitcnt lgkmcnt(0)
	v_mfma_f32_16x16x32_bf16 v[28:31], v[212:215], v[132:135], 0
	v_mfma_f32_16x16x32_bf16 v[32:35], v[220:223], v[132:135], 0
	v_mfma_f32_16x16x32_bf16 v[36:39], v[228:231], v[132:135], 0
	v_mfma_f32_16x16x32_bf16 v[28:31], v[216:219], v[136:139], v[28:31]
	v_mfma_f32_16x16x32_bf16 v[32:35], v[224:227], v[136:139], v[32:35]
	v_mfma_f32_16x16x32_bf16 v[36:39], v[232:235], v[136:139], v[36:39]
	ds_read2_b64 v[212:215], v187 offset0:8 offset1:12
	ds_read2_b64 v[216:219], v188 offset0:8 offset1:12
	ds_read2_b64 v[220:223], v189 offset0:8 offset1:12
	ds_read2_b64 v[224:227], v190 offset0:8 offset1:12
	ds_read2_b64 v[228:231], v187 offset0:16 offset1:20
	ds_read2_b64 v[232:235], v188 offset0:16 offset1:20
	ds_read2_b64 v[236:239], v189 offset0:16 offset1:20
	ds_read2_b64 v[240:243], v190 offset0:16 offset1:20
	s_add_i32 s27, s26, 5
	s_cmp_ge_i32 s27, 8
	s_cselect_b64 s[12:13], -1, 0
	s_or_b64 s[12:13], s[12:13], s[36:37]
	v_add_f32_e32 v16, v16, v99
	v_add_f32_e32 v17, v17, v98
	v_add_f32_e32 v18, v18, v97
	v_add_f32_e32 v19, v19, v96
	v_cndmask_b32_e64 v16, v195, v16, s[12:13]
	v_cndmask_b32_e64 v17, v195, v17, s[12:13]
	v_cndmask_b32_e64 v18, v195, v18, s[12:13]
	v_cndmask_b32_e64 v19, v195, v19, s[12:13]
	s_add_i32 s27, s26, 6
	s_cmp_ge_i32 s27, 8
	s_cselect_b64 s[2:3], -1, 0
	s_or_b64 s[2:3], s[2:3], s[36:37]
	v_add_f32_e32 v20, v20, v43
	v_add_f32_e32 v21, v21, v42
	v_add_f32_e32 v22, v22, v41
	v_add_f32_e32 v23, v23, v40
	v_cndmask_b32_e64 v20, v195, v20, s[2:3]
	v_cndmask_b32_e64 v21, v195, v21, s[2:3]
	v_cndmask_b32_e64 v22, v195, v22, s[2:3]
	v_cndmask_b32_e64 v23, v195, v23, s[2:3]
	s_add_i32 s27, s26, 7
	s_cmp_ge_i32 s27, 8
	s_cselect_b64 s[12:13], -1, 0
	s_or_b64 s[12:13], s[12:13], s[36:37]
	v_add_f32_e32 v24, v24, v75
	v_add_f32_e32 v25, v25, v74
	v_add_f32_e32 v26, v26, v73
	v_add_f32_e32 v27, v27, v72
	v_cndmask_b32_e64 v24, v195, v24, s[12:13]
	v_cndmask_b32_e64 v25, v195, v25, s[12:13]
	v_cndmask_b32_e64 v26, v195, v26, s[12:13]
	v_cndmask_b32_e64 v27, v195, v27, s[12:13]
	s_add_i32 s27, s26, 8
	s_cmp_ge_i32 s27, 8
	s_cselect_b64 s[2:3], -1, 0
	s_or_b64 s[2:3], s[2:3], s[36:37]
	v_add_f32_e32 v28, v28, v151
	v_add_f32_e32 v29, v29, v150
	v_add_f32_e32 v30, v30, v149
	v_add_f32_e32 v31, v31, v148
	v_cndmask_b32_e64 v28, v195, v28, s[2:3]
	v_cndmask_b32_e64 v29, v195, v29, s[2:3]
	v_cndmask_b32_e64 v30, v195, v30, s[2:3]
	v_cndmask_b32_e64 v31, v195, v31, s[2:3]
	s_add_i32 s27, s26, 9
	s_cmp_ge_i32 s27, 8
	s_cselect_b64 s[12:13], -1, 0
	s_or_b64 s[12:13], s[12:13], s[36:37]
	v_add_f32_e32 v32, v32, v155
	v_add_f32_e32 v33, v33, v154
	v_add_f32_e32 v34, v34, v153
	v_add_f32_e32 v35, v35, v152
	v_cndmask_b32_e64 v32, v195, v32, s[12:13]
	v_cndmask_b32_e64 v33, v195, v33, s[12:13]
	v_cndmask_b32_e64 v34, v195, v34, s[12:13]
	v_cndmask_b32_e64 v35, v195, v35, s[12:13]
	s_add_i32 s27, s26, 10
	s_cmp_ge_i32 s27, 8
	s_cselect_b64 s[2:3], -1, 0
	s_or_b64 s[2:3], s[2:3], s[36:37]
	s_andn2_b64 s[4:5], s[2:3], s[40:41]
	s_andn2_b64 s[6:7], s[2:3], s[42:43]
	s_andn2_b64 s[8:9], s[2:3], s[44:45]
	s_andn2_b64 s[10:11], s[2:3], s[46:47]
	v_add_f32_e32 v36, v36, v159
	v_add_f32_e32 v37, v37, v158
	v_add_f32_e32 v38, v38, v157
	v_add_f32_e32 v39, v39, v156
	v_cndmask_b32_e64 v36, v195, v36, s[4:5]
	v_cndmask_b32_e64 v37, v195, v37, s[6:7]
	v_cndmask_b32_e64 v38, v195, v38, s[8:9]
	v_cndmask_b32_e64 v39, v195, v39, s[10:11]
	v_max3_f32 v197, v4, v5, v184
	v_max3_f32 v197, v6, v7, v197
	v_max3_f32 v197, v8, v9, v197
	v_max3_f32 v197, v10, v11, v197
	v_max3_f32 v197, v12, v13, v197
	v_max3_f32 v197, v14, v15, v197
	v_max3_f32 v197, v16, v17, v197
	v_max3_f32 v197, v18, v19, v197
	v_max3_f32 v197, v20, v21, v197
	v_max3_f32 v197, v22, v23, v197
	v_max3_f32 v197, v24, v25, v197
	v_max3_f32 v197, v26, v27, v197
	v_max3_f32 v197, v28, v29, v197
	v_max3_f32 v197, v30, v31, v197
	v_max3_f32 v197, v32, v33, v197
	v_max3_f32 v197, v34, v35, v197
	v_max3_f32 v197, v36, v37, v197
	v_max3_f32 v197, v38, v39, v197
	ds_bpermute_b32 v0, v193, v197
	s_waitcnt lgkmcnt(0)
; __device__ __forceinline__ unsigned pkbf(float lo, float hi) { typedef float f2_t __attribute__((ext_vector_type(2))); typedef __bf16 b2_t __attribute__((ext_vector_type(2))); f2_t v = {lo, hi}; b2_t b = __builtin_convertvector(v, b2_t); return __builtin_bit_cast(unsigned, b); }
; #define MFMA16(a, b, c) __builtin_amdgcn_mfma_f32_16x16x32_bf16((a), (b), (c), 0, 0, 0)
; template <int PAR> __device__ __forceinline__ void attn_sub(const bf16* KS, const bf16* VT, const float* BTg, const float* gq, float sink2, int n, int ti, int hq, const u32x4 w0, const u32x4 w1, bf16* MIX, ss_t* ssb, int lane) {
;     ...
;     mx = fmaxf(mx, __shfl_xor(mx, 16)); mx = fmaxf(mx, __shfl_xor(mx, 32));
;     float lsum = 0.f;
; #pragma unroll
;     for (int t = 0; t < 10; ++t) { const int rel = t - PAR; if (rel < 0 || rel > 8) continue;
; #pragma unroll
;         for (int r = 0; r < 4; ++r) { const float p = __builtin_amdgcn_exp2f(sc[t][r] - mx); sc[t][r] = p; lsum += p; } }
;     lsum += __shfl_xor(lsum, 16); lsum += __shfl_xor(lsum, 32);
;     lsum += __builtin_amdgcn_exp2f(sink2 - mx);
;     const float rl = 1.0f / lsum;
;     f32x4 o[4];
; #pragma unroll
;     for (int dt = 0; dt < 4; ++dt) o[dt] = (f32x4){0.f, 0.f, 0.f, 0.f};
; #pragma unroll
;     for (int p = 0; p < 5; ++p) {
;         u32x4 pw; pw.x = pkbf(sc[2 * p][0], sc[2 * p][1]); pw.y = pkbf(sc[2 * p][2], sc[2 * p][3]); pw.z = pkbf(sc[2 * p + 1][0], sc[2 * p + 1][1]); pw.w = pkbf(sc[2 * p + 1][2], sc[2 * p + 1][3]);
;         const bf16x8 pb = __builtin_bit_cast(bf16x8, pw);
; #pragma unroll
;         for (int dt = 0; dt < 4; ++dt) {
;             const bf16* vp = VT + (16 * dt + fr) * VT_STRIDE + 16 * (tb + 2 * p) + 4 * fq;
;             const u32x2 lo = *(const u32x2*)vp, hi = *(const u32x2*)(vp + 16);
;             const u32x4 va = (u32x4){lo.x, lo.y, hi.x, hi.y};
;             o[dt] = MFMA16(__builtin_bit_cast(bf16x8, va), pb, o[dt]);
	v_max_f32_e32 v197, v197, v0
	ds_bpermute_b32 v0, v194, v197
	s_waitcnt lgkmcnt(0)
	v_max_f32_e32 v197, v197, v0
	v_sub_f32_e32 v4, v4, v197
	v_sub_f32_e32 v5, v5, v197
	v_sub_f32_e32 v6, v6, v197
	v_sub_f32_e32 v7, v7, v197
	v_sub_f32_e32 v8, v8, v197
	v_sub_f32_e32 v9, v9, v197
	v_sub_f32_e32 v10, v10, v197
	v_sub_f32_e32 v11, v11, v197
	v_sub_f32_e32 v12, v12, v197
	v_sub_f32_e32 v13, v13, v197
	v_sub_f32_e32 v14, v14, v197
	v_sub_f32_e32 v15, v15, v197
	v_sub_f32_e32 v16, v16, v197
	v_sub_f32_e32 v17, v17, v197
	v_sub_f32_e32 v18, v18, v197
	v_sub_f32_e32 v19, v19, v197
	v_sub_f32_e32 v20, v20, v197
	v_sub_f32_e32 v21, v21, v197
	v_sub_f32_e32 v22, v22, v197
	v_sub_f32_e32 v23, v23, v197
	v_sub_f32_e32 v24, v24, v197
	v_sub_f32_e32 v25, v25, v197
	v_sub_f32_e32 v26, v26, v197
	v_sub_f32_e32 v27, v27, v197
	v_sub_f32_e32 v28, v28, v197
	v_sub_f32_e32 v29, v29, v197
	v_sub_f32_e32 v30, v30, v197
	v_sub_f32_e32 v31, v31, v197
	v_sub_f32_e32 v32, v32, v197
	v_sub_f32_e32 v33, v33, v197
	v_sub_f32_e32 v34, v34, v197
	v_sub_f32_e32 v35, v35, v197
	v_sub_f32_e32 v36, v36, v197
	v_sub_f32_e32 v37, v37, v197
	v_sub_f32_e32 v38, v38, v197
	v_sub_f32_e32 v39, v39, v197
	v_sub_f32_e32 v0, v184, v197
	v_exp_f32_e32 v4, v4
	v_exp_f32_e32 v5, v5
	v_exp_f32_e32 v6, v6
	v_exp_f32_e32 v7, v7
	v_exp_f32_e32 v8, v8
	v_exp_f32_e32 v9, v9
	v_exp_f32_e32 v10, v10
	v_exp_f32_e32 v11, v11
	v_exp_f32_e32 v12, v12
	v_exp_f32_e32 v13, v13
	v_exp_f32_e32 v14, v14
	v_exp_f32_e32 v15, v15
	v_exp_f32_e32 v16, v16
	v_exp_f32_e32 v17, v17
	v_exp_f32_e32 v18, v18
	v_exp_f32_e32 v19, v19
	v_exp_f32_e32 v20, v20
	v_exp_f32_e32 v21, v21
	v_exp_f32_e32 v22, v22
	v_exp_f32_e32 v23, v23
	v_exp_f32_e32 v24, v24
	v_exp_f32_e32 v25, v25
	v_exp_f32_e32 v26, v26
	v_exp_f32_e32 v27, v27
	v_exp_f32_e32 v28, v28
	v_exp_f32_e32 v29, v29
	v_exp_f32_e32 v30, v30
	v_exp_f32_e32 v31, v31
	v_exp_f32_e32 v32, v32
	v_exp_f32_e32 v33, v33
	v_exp_f32_e32 v34, v34
	v_exp_f32_e32 v35, v35
	v_exp_f32_e32 v36, v36
	v_exp_f32_e32 v37, v37
	v_exp_f32_e32 v38, v38
	v_exp_f32_e32 v39, v39
	v_exp_f32_e32 v0, v0
	v_pk_add_f32 v[78:79], v[4:5], v[6:7]
	v_pk_add_f32 v[78:79], v[78:79], v[8:9]
	v_pk_add_f32 v[78:79], v[78:79], v[10:11]
	v_pk_add_f32 v[78:79], v[78:79], v[12:13]
	v_pk_add_f32 v[78:79], v[78:79], v[14:15]
	v_pk_add_f32 v[78:79], v[78:79], v[16:17]
	v_pk_add_f32 v[78:79], v[78:79], v[18:19]
	v_pk_add_f32 v[78:79], v[78:79], v[20:21]
	v_pk_add_f32 v[78:79], v[78:79], v[22:23]
	v_pk_add_f32 v[78:79], v[78:79], v[24:25]
	v_pk_add_f32 v[78:79], v[78:79], v[26:27]
	v_pk_add_f32 v[78:79], v[78:79], v[28:29]
	v_pk_add_f32 v[78:79], v[78:79], v[30:31]
	v_pk_add_f32 v[78:79], v[78:79], v[32:33]
	v_pk_add_f32 v[78:79], v[78:79], v[34:35]
	v_pk_add_f32 v[78:79], v[78:79], v[36:37]
	v_pk_add_f32 v[78:79], v[78:79], v[38:39]
	v_add_f32_e32 v1, v78, v79
	ds_bpermute_b32 v3, v193, v1
	s_waitcnt lgkmcnt(0)
	v_add_f32_e32 v1, v1, v3
	ds_bpermute_b32 v3, v194, v1
	s_waitcnt lgkmcnt(0)
	v_add_f32_e32 v1, v1, v3
	v_add_f32_e32 v1, v1, v0
	v_rcp_f32_e32 v198, v1
	v_cvt_pk_bf16_f32 v64, v4, v5
	v_cvt_pk_bf16_f32 v65, v6, v7
	v_cvt_pk_bf16_f32 v66, v8, v9
	v_cvt_pk_bf16_f32 v67, v10, v11
	s_nop 1
	v_mfma_f32_16x16x32_bf16 v[48:51], v[212:215], v[64:67], 0
	v_mfma_f32_16x16x32_bf16 v[52:55], v[216:219], v[64:67], 0
	v_mfma_f32_16x16x32_bf16 v[56:59], v[220:223], v[64:67], 0
	v_mfma_f32_16x16x32_bf16 v[60:63], v[224:227], v[64:67], 0
	ds_read2_b64 v[212:215], v187 offset0:24 offset1:28
	ds_read2_b64 v[216:219], v188 offset0:24 offset1:28
	ds_read2_b64 v[220:223], v189 offset0:24 offset1:28
	ds_read2_b64 v[224:227], v190 offset0:24 offset1:28
	v_cvt_pk_bf16_f32 v68, v12, v13
	v_cvt_pk_bf16_f32 v69, v14, v15
	v_cvt_pk_bf16_f32 v70, v16, v17
	v_cvt_pk_bf16_f32 v71, v18, v19
	s_nop 1
	v_mfma_f32_16x16x32_bf16 v[48:51], v[228:231], v[68:71], v[48:51]
	v_mfma_f32_16x16x32_bf16 v[52:55], v[232:235], v[68:71], v[52:55]
	v_mfma_f32_16x16x32_bf16 v[56:59], v[236:239], v[68:71], v[56:59]
	v_mfma_f32_16x16x32_bf16 v[60:63], v[240:243], v[68:71], v[60:63]
	ds_read2_b64 v[228:231], v187 offset0:32 offset1:36
	ds_read2_b64 v[232:235], v188 offset0:32 offset1:36
	ds_read2_b64 v[236:239], v189 offset0:32 offset1:36
	ds_read2_b64 v[240:243], v190 offset0:32 offset1:36
	v_cvt_pk_bf16_f32 v64, v20, v21
	v_cvt_pk_bf16_f32 v65, v22, v23
	v_cvt_pk_bf16_f32 v66, v24, v25
	v_cvt_pk_bf16_f32 v67, v26, v27
	s_waitcnt lgkmcnt(0)
	s_nop 1
	v_mfma_f32_16x16x32_bf16 v[48:51], v[212:215], v[64:67], v[48:51]
	v_mfma_f32_16x16x32_bf16 v[52:55], v[216:219], v[64:67], v[52:55]
	v_mfma_f32_16x16x32_bf16 v[56:59], v[220:223], v[64:67], v[56:59]
	v_mfma_f32_16x16x32_bf16 v[60:63], v[224:227], v[64:67], v[60:63]
	ds_read_b64 v[212:213], v187 offset:320
	ds_read_b64 v[216:217], v188 offset:320
	ds_read_b64 v[220:221], v189 offset:320
	ds_read_b64 v[224:225], v190 offset:320
	v_cvt_pk_bf16_f32 v68, v28, v29
	v_cvt_pk_bf16_f32 v69, v30, v31
	v_cvt_pk_bf16_f32 v70, v32, v33
	v_cvt_pk_bf16_f32 v71, v34, v35
	s_waitcnt lgkmcnt(0)
	s_nop 1
	v_mfma_f32_16x16x32_bf16 v[48:51], v[228:231], v[68:71], v[48:51]
	v_mfma_f32_16x16x32_bf16 v[52:55], v[232:235], v[68:71], v[52:55]
	v_mfma_f32_16x16x32_bf16 v[56:59], v[236:239], v[68:71], v[56:59]
	v_mfma_f32_16x16x32_bf16 v[60:63], v[240:243], v[68:71], v[60:63]
	v_cvt_pk_bf16_f32 v64, v36, v37
	v_cvt_pk_bf16_f32 v65, v38, v39
	v_mov_b32_e32 v66, 0
	v_mov_b32_e32 v67, 0
	s_waitcnt lgkmcnt(0)
; __device__ __forceinline__ void ss_add(ss_t* p, float sq) { const float fl = floorf(sq); const unsigned hi = (unsigned)fl, lo = (unsigned)((sq - fl) * 4294967296.0f); atomicAdd(p, ((ss_t)hi << 32) | (ss_t)lo); }
; template <int PAR> __device__ __forceinline__ void attn_sub(const bf16* KS, const bf16* VT, const float* BTg, const float* gq, float sink2, int n, int ti, int hq, const u32x4 w0, const u32x4 w1, bf16* MIX, ss_t* ssb, int lane) {
;     ...
;     for (int t = 0; t < 10; ++t) {
;         constexpr int dummy = 0; (void)dummy;
;         const int rel = t - PAR;
;         if (rel < 0 || rel > 8) { sc[t] = (f32x4){0.f, 0.f, 0.f, 0.f}; continue; }
;         const bf16* kp = KS + (16 * (tb + t) + fr) * KS_STRIDE + 8 * fq;
;         const bf16x8 k0 = *(const bf16x8*)kp, k1 = *(const bf16x8*)(kp + 32);
;         f32x4 acc = (f32x4){0.f, 0.f, 0.f, 0.f};
;         acc = MFMA16(k0, qf[0], acc); acc = MFMA16(k1, qf[1], acc);
;         const bool tv = (n > 0) || (tb + t >= 8);
; #pragma unroll
;         for (int r = 0; r < 4; ++r) { bool valid = tv; if (rel == 0) valid = valid && (e0 + r >= 1); if (rel == 8) valid = valid && (e0 + r <= 0);
;             const float v = valid ? acc[r] + bp[16 * (8 - rel) + (3 - r)] : -1e30f; acc[r] = v; mx = fmaxf(mx, v); }
;     ...
;     for (int p = 0; p < 5; ++p) {
;         u32x4 pw; pw.x = pkbf(sc[2 * p][0], sc[2 * p][1]); pw.y = pkbf(sc[2 * p][2], sc[2 * p][3]); pw.z = pkbf(sc[2 * p + 1][0], sc[2 * p + 1][1]); pw.w = pkbf(sc[2 * p + 1][2], sc[2 * p + 1][3]);
;         const bf16x8 pb = __builtin_bit_cast(bf16x8, pw);
; #pragma unroll
;         for (int dt = 0; dt < 4; ++dt) {
;             const bf16* vp = VT + (16 * dt + fr) * VT_STRIDE + 16 * (tb + 2 * p) + 4 * fq;
;             const u32x2 lo = *(const u32x2*)vp, hi = *(const u32x2*)(vp + 16);
;             const u32x4 va = (u32x4){lo.x, lo.y, hi.x, hi.y};
;             o[dt] = MFMA16(__builtin_bit_cast(bf16x8, va), pb, o[dt]);
;         }
;     }
;     bf16* op = MIX + (size_t)tok * DM + 1024 + hq * 64 + 4 * fq;
;     float sq = 0.f;
; #pragma unroll
;     for (int dt = 0; dt < 4; ++dt) { const f32x4 v = o[dt] * rl; sq += (v[0] * v[0] + v[1] * v[1]) + (v[2] * v[2] + v[3] * v[3]); u32x2 w; w.x = pkbf(v[0], v[1]); w.y = pkbf(v[2], v[3]); *(u32x2*)(op + 16 * dt) = w; }
;     sq += __shfl_xor(sq, 16); sq += __shfl_xor(sq, 32); if (fq == 0) ss_add(ssb + tok, sq);
	v_mov_b32_e32 v214, 0
	v_mov_b32_e32 v215, 0
	v_mov_b32_e32 v218, 0
	v_mov_b32_e32 v219, 0
	v_mov_b32_e32 v222, 0
	v_mov_b32_e32 v223, 0
	v_mov_b32_e32 v226, 0
	v_mov_b32_e32 v227, 0
	s_nop 1
	v_mfma_f32_16x16x32_bf16 v[48:51], v[212:215], v[64:67], v[48:51]
	v_mfma_f32_16x16x32_bf16 v[52:55], v[216:219], v[64:67], v[52:55]
	v_mfma_f32_16x16x32_bf16 v[56:59], v[220:223], v[64:67], v[56:59]
	v_mfma_f32_16x16x32_bf16 v[60:63], v[224:227], v[64:67], v[60:63]
	s_nop 7
	s_nop 1
	v_pk_mul_f32 v[48:49], v[198:199], v[48:49] op_sel_hi:[0,1]
	v_pk_mul_f32 v[50:51], v[198:199], v[50:51] op_sel_hi:[0,1]
	v_pk_mul_f32 v[52:53], v[198:199], v[52:53] op_sel_hi:[0,1]
	v_pk_mul_f32 v[54:55], v[198:199], v[54:55] op_sel_hi:[0,1]
	v_pk_mul_f32 v[56:57], v[198:199], v[56:57] op_sel_hi:[0,1]
	v_pk_mul_f32 v[58:59], v[198:199], v[58:59] op_sel_hi:[0,1]
	v_pk_mul_f32 v[60:61], v[198:199], v[60:61] op_sel_hi:[0,1]
	v_pk_mul_f32 v[62:63], v[198:199], v[62:63] op_sel_hi:[0,1]
	v_pk_mul_f32 v[80:81], v[48:49], v[48:49]
	v_pk_fma_f32 v[80:81], v[50:51], v[50:51], v[80:81]
	v_pk_fma_f32 v[80:81], v[52:53], v[52:53], v[80:81]
	v_pk_fma_f32 v[80:81], v[54:55], v[54:55], v[80:81]
	v_pk_fma_f32 v[80:81], v[56:57], v[56:57], v[80:81]
	v_pk_fma_f32 v[80:81], v[58:59], v[58:59], v[80:81]
	v_pk_fma_f32 v[80:81], v[60:61], v[60:61], v[80:81]
	v_pk_fma_f32 v[80:81], v[62:63], v[62:63], v[80:81]
	v_add_f32_e32 v0, v80, v81
	ds_bpermute_b32 v1, v193, v0
	v_cvt_pk_bf16_f32 v48, v48, v49
	v_cvt_pk_bf16_f32 v49, v50, v51
	global_store_dwordx2 v191, v[48:49], s[100:101] offset:0
	v_cvt_pk_bf16_f32 v52, v52, v53
	v_cvt_pk_bf16_f32 v53, v54, v55
	global_store_dwordx2 v191, v[52:53], s[100:101] offset:32
	v_cvt_pk_bf16_f32 v56, v56, v57
	v_cvt_pk_bf16_f32 v57, v58, v59
	global_store_dwordx2 v191, v[56:57], s[100:101] offset:64
	v_cvt_pk_bf16_f32 v60, v60, v61
	v_cvt_pk_bf16_f32 v61, v62, v63
	global_store_dwordx2 v191, v[60:61], s[100:101] offset:96
	s_waitcnt lgkmcnt(0)
	v_add_f32_e32 v0, v0, v1
	ds_bpermute_b32 v1, v194, v0
	s_waitcnt lgkmcnt(0)
	v_add_f32_e32 v0, v0, v1
	s_mov_b64 exec, s[56:57]
	v_floor_f32_e32 v1, v0
	v_sub_f32_e32 v0, v0, v1
	v_mul_f32_e32 v0, 0x4f800000, v0
	v_cvt_u32_f32_e32 v47, v1
	v_cvt_u32_f32_e32 v46, v0
	global_atomic_add_x2 v192, v[46:47], s[100:101] offset:256
	s_mov_b64 exec, -1
	v_add_u32_e32 v191, 0x10000, v191
	ds_read_b128 v[212:215], v185 offset:6912
	ds_read_b128 v[216:219], v185 offset:6976
	ds_read_b128 v[220:223], v185 offset:9216
	ds_read_b128 v[224:227], v185 offset:9280
	ds_read_b128 v[228:231], v185 offset:11520
	ds_read_b128 v[232:235], v185 offset:11584
	ds_read_b128 v[48:51], v185 offset:13824
	ds_read_b128 v[52:55], v185 offset:13888
	ds_read_b128 v[56:59], v185 offset:16128
	ds_read_b128 v[60:63], v185 offset:16192
	ds_read_b128 v[64:67], v185 offset:18432
	ds_read_b128 v[68:71], v185 offset:18496
	s_waitcnt lgkmcnt(6)
	v_mfma_f32_16x16x32_bf16 v[4:7], v[212:215], v[140:143], 0
	v_mfma_f32_16x16x32_bf16 v[8:11], v[220:223], v[140:143], 0
	v_mfma_f32_16x16x32_bf16 v[12:15], v[228:231], v[140:143], 0
	v_mfma_f32_16x16x32_bf16 v[4:7], v[216:219], v[144:147], v[4:7]
	v_mfma_f32_16x16x32_bf16 v[8:11], v[224:227], v[144:147], v[8:11]
	v_mfma_f32_16x16x32_bf16 v[12:15], v[232:235], v[144:147], v[12:15]
	ds_read_b128 v[212:215], v185 offset:20736
	ds_read_b128 v[216:219], v185 offset:20800
	ds_read_b128 v[220:223], v185 offset:23040
	ds_read_b128 v[224:227], v185 offset:23104
	ds_read_b128 v[228:231], v185 offset:25344
	ds_read_b128 v[232:235], v185 offset:25408
	s_waitcnt lgkmcnt(6)
	v_mfma_f32_16x16x32_bf16 v[16:19], v[48:51], v[140:143], 0
	v_mfma_f32_16x16x32_bf16 v[20:23], v[56:59], v[140:143], 0
	v_mfma_f32_16x16x32_bf16 v[24:27], v[64:67], v[140:143], 0
	v_mfma_f32_16x16x32_bf16 v[16:19], v[52:55], v[144:147], v[16:19]
	v_mfma_f32_16x16x32_bf16 v[20:23], v[60:63], v[144:147], v[20:23]
	v_mfma_f32_16x16x32_bf16 v[24:27], v[68:71], v[144:147], v[24:27]
	s_add_i32 s27, s26, 3
	s_cmp_ge_i32 s27, 8
	s_cselect_b64 s[2:3], -1, 0
	s_or_b64 s[2:3], s[2:3], s[36:37]
	s_and_b64 s[4:5], s[2:3], s[40:41]
	s_and_b64 s[6:7], s[2:3], s[42:43]
	s_and_b64 s[8:9], s[2:3], s[44:45]
	s_and_b64 s[10:11], s[2:3], s[46:47]
	v_add_f32_e32 v4, v4, v87
	v_add_f32_e32 v5, v5, v86
	v_add_f32_e32 v6, v6, v85
	v_add_f32_e32 v7, v7, v84
	v_cndmask_b32_e64 v4, v195, v4, s[4:5]
	v_cndmask_b32_e64 v5, v195, v5, s[6:7]
	v_cndmask_b32_e64 v6, v195, v6, s[8:9]
	v_cndmask_b32_e64 v7, v195, v7, s[10:11]
	s_add_i32 s27, s26, 4
	s_cmp_ge_i32 s27, 8
	s_cselect_b64 s[12:13], -1, 0
	s_or_b64 s[12:13], s[12:13], s[36:37]
	v_add_f32_e32 v8, v8, v91
	v_add_f32_e32 v9, v9, v90
	v_add_f32_e32 v10, v10, v89
	v_add_f32_e32 v11, v11, v88
	v_cndmask_b32_e64 v8, v195, v8, s[12:13]
	v_cndmask_b32_e64 v9, v195, v9, s[12:13]
	v_cndmask_b32_e64 v10, v195, v10, s[12:13]
	v_cndmask_b32_e64 v11, v195, v11, s[12:13]
	s_add_i32 s27, s26, 5
	s_cmp_ge_i32 s27, 8
	s_cselect_b64 s[2:3], -1, 0
	s_or_b64 s[2:3], s[2:3], s[36:37]
	v_add_f32_e32 v12, v12, v95
	v_add_f32_e32 v13, v13, v94
	v_add_f32_e32 v14, v14, v93
	v_add_f32_e32 v15, v15, v92
	v_cndmask_b32_e64 v12, v195, v12, s[2:3]
	v_cndmask_b32_e64 v13, v195, v13, s[2:3]
	v_cndmask_b32_e64 v14, v195, v14, s[2:3]
	v_cndmask_b32_e64 v15, v195, v15, s[2:3]
	s_waitcnt lgkmcnt(0)
; #define MFMA16(a, b, c) __builtin_amdgcn_mfma_f32_16x16x32_bf16((a), (b), (c), 0, 0, 0)
; template <int PAR> __device__ __forceinline__ void attn_sub(const bf16* KS, const bf16* VT, const float* BTg, const float* gq, float sink2, int n, int ti, int hq, const u32x4 w0, const u32x4 w1, bf16* MIX, ss_t* ssb, int lane) {
;     ...
;     for (int t = 0; t < 10; ++t) {
;         constexpr int dummy = 0; (void)dummy;
;         const int rel = t - PAR;
;         if (rel < 0 || rel > 8) { sc[t] = (f32x4){0.f, 0.f, 0.f, 0.f}; continue; }
;         const bf16* kp = KS + (16 * (tb + t) + fr) * KS_STRIDE + 8 * fq;
;         const bf16x8 k0 = *(const bf16x8*)kp, k1 = *(const bf16x8*)(kp + 32);
;         f32x4 acc = (f32x4){0.f, 0.f, 0.f, 0.f};
;         acc = MFMA16(k0, qf[0], acc); acc = MFMA16(k1, qf[1], acc);
;         const bool tv = (n > 0) || (tb + t >= 8);
; #pragma unroll
;         for (int r = 0; r < 4; ++r) { bool valid = tv; if (rel == 0) valid = valid && (e0 + r >= 1); if (rel == 8) valid = valid && (e0 + r <= 0);
;             const float v = valid ? acc[r] + bp[16 * (8 - rel) + (3 - r)] : -1e30f; acc[r] = v; mx = fmaxf(mx, v); }
;         sc[t] = acc;
;     }
;     mx = fmaxf(mx, __shfl_xor(mx, 16)); mx = fmaxf(mx, __shfl_xor(mx, 32));
;     float lsum = 0.f;
; #pragma unroll
;     for (int t = 0; t < 10; ++t) { const int rel = t - PAR; if (rel < 0 || rel > 8) continue;
; #pragma unroll
;         for (int r = 0; r < 4; ++r) { const float p = __builtin_amdgcn_exp2f(sc[t][r] - mx); sc[t][r] = p; lsum += p; } }
;     lsum += __shfl_xor(lsum, 16); lsum += __shfl_xor(lsum, 32);
	v_mfma_f32_16x16x32_bf16 v[28:31], v[212:215], v[140:143], 0
	v_mfma_f32_16x16x32_bf16 v[32:35], v[220:223], v[140:143], 0
	v_mfma_f32_16x16x32_bf16 v[36:39], v[228:231], v[140:143], 0
	v_mfma_f32_16x16x32_bf16 v[28:31], v[216:219], v[144:147], v[28:31]
	v_mfma_f32_16x16x32_bf16 v[32:35], v[224:227], v[144:147], v[32:35]
	v_mfma_f32_16x16x32_bf16 v[36:39], v[232:235], v[144:147], v[36:39]
	ds_read2_b64 v[212:215], v187 offset0:12 offset1:16
	ds_read2_b64 v[216:219], v188 offset0:12 offset1:16
	ds_read2_b64 v[220:223], v189 offset0:12 offset1:16
	ds_read2_b64 v[224:227], v190 offset0:12 offset1:16
	ds_read2_b64 v[228:231], v187 offset0:20 offset1:24
	ds_read2_b64 v[232:235], v188 offset0:20 offset1:24
	ds_read2_b64 v[236:239], v189 offset0:20 offset1:24
	ds_read2_b64 v[240:243], v190 offset0:20 offset1:24
	s_add_i32 s27, s26, 6
	s_cmp_ge_i32 s27, 8
	s_cselect_b64 s[12:13], -1, 0
	s_or_b64 s[12:13], s[12:13], s[36:37]
	v_add_f32_e32 v16, v16, v99
	v_add_f32_e32 v17, v17, v98
	v_add_f32_e32 v18, v18, v97
	v_add_f32_e32 v19, v19, v96
	v_cndmask_b32_e64 v16, v195, v16, s[12:13]
	v_cndmask_b32_e64 v17, v195, v17, s[12:13]
	v_cndmask_b32_e64 v18, v195, v18, s[12:13]
	v_cndmask_b32_e64 v19, v195, v19, s[12:13]
	s_add_i32 s27, s26, 7
	s_cmp_ge_i32 s27, 8
	s_cselect_b64 s[2:3], -1, 0
	s_or_b64 s[2:3], s[2:3], s[36:37]
	v_add_f32_e32 v20, v20, v43
	v_add_f32_e32 v21, v21, v42
	v_add_f32_e32 v22, v22, v41
	v_add_f32_e32 v23, v23, v40
	v_cndmask_b32_e64 v20, v195, v20, s[2:3]
	v_cndmask_b32_e64 v21, v195, v21, s[2:3]
	v_cndmask_b32_e64 v22, v195, v22, s[2:3]
	v_cndmask_b32_e64 v23, v195, v23, s[2:3]
	s_add_i32 s27, s26, 8
	s_cmp_ge_i32 s27, 8
	s_cselect_b64 s[12:13], -1, 0
	s_or_b64 s[12:13], s[12:13], s[36:37]
	v_add_f32_e32 v24, v24, v75
	v_add_f32_e32 v25, v25, v74
	v_add_f32_e32 v26, v26, v73
	v_add_f32_e32 v27, v27, v72
	v_cndmask_b32_e64 v24, v195, v24, s[12:13]
	v_cndmask_b32_e64 v25, v195, v25, s[12:13]
	v_cndmask_b32_e64 v26, v195, v26, s[12:13]
	v_cndmask_b32_e64 v27, v195, v27, s[12:13]
	s_add_i32 s27, s26, 9
	s_cmp_ge_i32 s27, 8
	s_cselect_b64 s[2:3], -1, 0
	s_or_b64 s[2:3], s[2:3], s[36:37]
	v_add_f32_e32 v28, v28, v151
	v_add_f32_e32 v29, v29, v150
	v_add_f32_e32 v30, v30, v149
	v_add_f32_e32 v31, v31, v148
	v_cndmask_b32_e64 v28, v195, v28, s[2:3]
	v_cndmask_b32_e64 v29, v195, v29, s[2:3]
	v_cndmask_b32_e64 v30, v195, v30, s[2:3]
	v_cndmask_b32_e64 v31, v195, v31, s[2:3]
	s_add_i32 s27, s26, 10
	s_cmp_ge_i32 s27, 8
	s_cselect_b64 s[12:13], -1, 0
	s_or_b64 s[12:13], s[12:13], s[36:37]
	v_add_f32_e32 v32, v32, v155
	v_add_f32_e32 v33, v33, v154
	v_add_f32_e32 v34, v34, v153
	v_add_f32_e32 v35, v35, v152
	v_cndmask_b32_e64 v32, v195, v32, s[12:13]
	v_cndmask_b32_e64 v33, v195, v33, s[12:13]
	v_cndmask_b32_e64 v34, v195, v34, s[12:13]
	v_cndmask_b32_e64 v35, v195, v35, s[12:13]
	s_add_i32 s27, s26, 11
	s_cmp_ge_i32 s27, 8
	s_cselect_b64 s[2:3], -1, 0
	s_or_b64 s[2:3], s[2:3], s[36:37]
	s_andn2_b64 s[4:5], s[2:3], s[40:41]
	s_andn2_b64 s[6:7], s[2:3], s[42:43]
	s_andn2_b64 s[8:9], s[2:3], s[44:45]
	s_andn2_b64 s[10:11], s[2:3], s[46:47]
	v_add_f32_e32 v36, v36, v159
	v_add_f32_e32 v37, v37, v158
	v_add_f32_e32 v38, v38, v157
	v_add_f32_e32 v39, v39, v156
	v_cndmask_b32_e64 v36, v195, v36, s[4:5]
	v_cndmask_b32_e64 v37, v195, v37, s[6:7]
	v_cndmask_b32_e64 v38, v195, v38, s[8:9]
	v_cndmask_b32_e64 v39, v195, v39, s[10:11]
	v_max3_f32 v197, v4, v5, v184
	v_max3_f32 v197, v6, v7, v197
	v_max3_f32 v197, v8, v9, v197
	v_max3_f32 v197, v10, v11, v197
	v_max3_f32 v197, v12, v13, v197
	v_max3_f32 v197, v14, v15, v197
	v_max3_f32 v197, v16, v17, v197
	v_max3_f32 v197, v18, v19, v197
	v_max3_f32 v197, v20, v21, v197
	v_max3_f32 v197, v22, v23, v197
	v_max3_f32 v197, v24, v25, v197
	v_max3_f32 v197, v26, v27, v197
	v_max3_f32 v197, v28, v29, v197
	v_max3_f32 v197, v30, v31, v197
	v_max3_f32 v197, v32, v33, v197
	v_max3_f32 v197, v34, v35, v197
	v_max3_f32 v197, v36, v37, v197
	v_max3_f32 v197, v38, v39, v197
	ds_bpermute_b32 v0, v193, v197
	s_waitcnt lgkmcnt(0)
	v_max_f32_e32 v197, v197, v0
	ds_bpermute_b32 v0, v194, v197
	s_waitcnt lgkmcnt(0)
	v_max_f32_e32 v197, v197, v0
	v_sub_f32_e32 v4, v4, v197
	v_sub_f32_e32 v5, v5, v197
	v_sub_f32_e32 v6, v6, v197
	v_sub_f32_e32 v7, v7, v197
	v_sub_f32_e32 v8, v8, v197
	v_sub_f32_e32 v9, v9, v197
	v_sub_f32_e32 v10, v10, v197
	v_sub_f32_e32 v11, v11, v197
	v_sub_f32_e32 v12, v12, v197
	v_sub_f32_e32 v13, v13, v197
	v_sub_f32_e32 v14, v14, v197
	v_sub_f32_e32 v15, v15, v197
	v_sub_f32_e32 v16, v16, v197
	v_sub_f32_e32 v17, v17, v197
	v_sub_f32_e32 v18, v18, v197
	v_sub_f32_e32 v19, v19, v197
	v_sub_f32_e32 v20, v20, v197
	v_sub_f32_e32 v21, v21, v197
	v_sub_f32_e32 v22, v22, v197
	v_sub_f32_e32 v23, v23, v197
	v_sub_f32_e32 v24, v24, v197
	v_sub_f32_e32 v25, v25, v197
	v_sub_f32_e32 v26, v26, v197
	v_sub_f32_e32 v27, v27, v197
	v_sub_f32_e32 v28, v28, v197
	v_sub_f32_e32 v29, v29, v197
	v_sub_f32_e32 v30, v30, v197
	v_sub_f32_e32 v31, v31, v197
	v_sub_f32_e32 v32, v32, v197
	v_sub_f32_e32 v33, v33, v197
	v_sub_f32_e32 v34, v34, v197
	v_sub_f32_e32 v35, v35, v197
	v_sub_f32_e32 v36, v36, v197
	v_sub_f32_e32 v37, v37, v197
	v_sub_f32_e32 v38, v38, v197
	v_sub_f32_e32 v39, v39, v197
	v_sub_f32_e32 v0, v184, v197
	v_exp_f32_e32 v4, v4
	v_exp_f32_e32 v5, v5
	v_exp_f32_e32 v6, v6
	v_exp_f32_e32 v7, v7
	v_exp_f32_e32 v8, v8
	v_exp_f32_e32 v9, v9
	v_exp_f32_e32 v10, v10
	v_exp_f32_e32 v11, v11
	v_exp_f32_e32 v12, v12
	v_exp_f32_e32 v13, v13
	v_exp_f32_e32 v14, v14
	v_exp_f32_e32 v15, v15
	v_exp_f32_e32 v16, v16
	v_exp_f32_e32 v17, v17
	v_exp_f32_e32 v18, v18
	v_exp_f32_e32 v19, v19
	v_exp_f32_e32 v20, v20
	v_exp_f32_e32 v21, v21
	v_exp_f32_e32 v22, v22
	v_exp_f32_e32 v23, v23
	v_exp_f32_e32 v24, v24
	v_exp_f32_e32 v25, v25
	v_exp_f32_e32 v26, v26
	v_exp_f32_e32 v27, v27
	v_exp_f32_e32 v28, v28
	v_exp_f32_e32 v29, v29
	v_exp_f32_e32 v30, v30
	v_exp_f32_e32 v31, v31
	v_exp_f32_e32 v32, v32
	v_exp_f32_e32 v33, v33
	v_exp_f32_e32 v34, v34
	v_exp_f32_e32 v35, v35
	v_exp_f32_e32 v36, v36
	v_exp_f32_e32 v37, v37
	v_exp_f32_e32 v38, v38
	v_exp_f32_e32 v39, v39
	v_exp_f32_e32 v0, v0
	v_pk_add_f32 v[78:79], v[4:5], v[6:7]
	v_pk_add_f32 v[78:79], v[78:79], v[8:9]
	v_pk_add_f32 v[78:79], v[78:79], v[10:11]
	v_pk_add_f32 v[78:79], v[78:79], v[12:13]
	v_pk_add_f32 v[78:79], v[78:79], v[14:15]
	v_pk_add_f32 v[78:79], v[78:79], v[16:17]
	v_pk_add_f32 v[78:79], v[78:79], v[18:19]
	v_pk_add_f32 v[78:79], v[78:79], v[20:21]
	v_pk_add_f32 v[78:79], v[78:79], v[22:23]
	v_pk_add_f32 v[78:79], v[78:79], v[24:25]
	v_pk_add_f32 v[78:79], v[78:79], v[26:27]
	v_pk_add_f32 v[78:79], v[78:79], v[28:29]
	v_pk_add_f32 v[78:79], v[78:79], v[30:31]
	v_pk_add_f32 v[78:79], v[78:79], v[32:33]
	v_pk_add_f32 v[78:79], v[78:79], v[34:35]
	v_pk_add_f32 v[78:79], v[78:79], v[36:37]
	v_pk_add_f32 v[78:79], v[78:79], v[38:39]
	v_add_f32_e32 v1, v78, v79
	ds_bpermute_b32 v3, v193, v1
	s_waitcnt lgkmcnt(0)
; __device__ __forceinline__ void ss_add(ss_t* p, float sq) { const float fl = floorf(sq); const unsigned hi = (unsigned)fl, lo = (unsigned)((sq - fl) * 4294967296.0f); atomicAdd(p, ((ss_t)hi << 32) | (ss_t)lo); }
; __device__ __forceinline__ unsigned pkbf(float lo, float hi) { typedef float f2_t __attribute__((ext_vector_type(2))); typedef __bf16 b2_t __attribute__((ext_vector_type(2))); f2_t v = {lo, hi}; b2_t b = __builtin_convertvector(v, b2_t); return __builtin_bit_cast(unsigned, b); }
; #define MFMA16(a, b, c) __builtin_amdgcn_mfma_f32_16x16x32_bf16((a), (b), (c), 0, 0, 0)
; template <int PAR> __device__ __forceinline__ void attn_sub(const bf16* KS, const bf16* VT, const float* BTg, const float* gq, float sink2, int n, int ti, int hq, const u32x4 w0, const u32x4 w1, bf16* MIX, ss_t* ssb, int lane) {
;     ...
;     for (int p = 0; p < 5; ++p) {
;         u32x4 pw; pw.x = pkbf(sc[2 * p][0], sc[2 * p][1]); pw.y = pkbf(sc[2 * p][2], sc[2 * p][3]); pw.z = pkbf(sc[2 * p + 1][0], sc[2 * p + 1][1]); pw.w = pkbf(sc[2 * p + 1][2], sc[2 * p + 1][3]);
;         const bf16x8 pb = __builtin_bit_cast(bf16x8, pw);
; #pragma unroll
;         for (int dt = 0; dt < 4; ++dt) {
;             const bf16* vp = VT + (16 * dt + fr) * VT_STRIDE + 16 * (tb + 2 * p) + 4 * fq;
;             const u32x2 lo = *(const u32x2*)vp, hi = *(const u32x2*)(vp + 16);
;             const u32x4 va = (u32x4){lo.x, lo.y, hi.x, hi.y};
;             o[dt] = MFMA16(__builtin_bit_cast(bf16x8, va), pb, o[dt]);
;         }
;     }
;     bf16* op = MIX + (size_t)tok * DM + 1024 + hq * 64 + 4 * fq;
;     float sq = 0.f;
; #pragma unroll
;     for (int dt = 0; dt < 4; ++dt) { const f32x4 v = o[dt] * rl; sq += (v[0] * v[0] + v[1] * v[1]) + (v[2] * v[2] + v[3] * v[3]); u32x2 w; w.x = pkbf(v[0], v[1]); w.y = pkbf(v[2], v[3]); *(u32x2*)(op + 16 * dt) = w; }
;     sq += __shfl_xor(sq, 16); sq += __shfl_xor(sq, 32); if (fq == 0) ss_add(ssb + tok, sq);
	v_add_f32_e32 v1, v1, v3
	ds_bpermute_b32 v3, v194, v1
	s_waitcnt lgkmcnt(0)
	v_add_f32_e32 v1, v1, v3
	v_add_f32_e32 v1, v1, v0
	v_rcp_f32_e32 v198, v1
	v_cvt_pk_bf16_f32 v64, v4, v5
	v_cvt_pk_bf16_f32 v65, v6, v7
	v_cvt_pk_bf16_f32 v66, v8, v9
	v_cvt_pk_bf16_f32 v67, v10, v11
	s_nop 1
	v_mfma_f32_16x16x32_bf16 v[48:51], v[212:215], v[64:67], 0
	v_mfma_f32_16x16x32_bf16 v[52:55], v[216:219], v[64:67], 0
	v_mfma_f32_16x16x32_bf16 v[56:59], v[220:223], v[64:67], 0
	v_mfma_f32_16x16x32_bf16 v[60:63], v[224:227], v[64:67], 0
	ds_read2_b64 v[212:215], v187 offset0:28 offset1:32
	ds_read2_b64 v[216:219], v188 offset0:28 offset1:32
	ds_read2_b64 v[220:223], v189 offset0:28 offset1:32
	ds_read2_b64 v[224:227], v190 offset0:28 offset1:32
	v_cvt_pk_bf16_f32 v68, v12, v13
	v_cvt_pk_bf16_f32 v69, v14, v15
	v_cvt_pk_bf16_f32 v70, v16, v17
	v_cvt_pk_bf16_f32 v71, v18, v19
	s_nop 1
	v_mfma_f32_16x16x32_bf16 v[48:51], v[228:231], v[68:71], v[48:51]
	v_mfma_f32_16x16x32_bf16 v[52:55], v[232:235], v[68:71], v[52:55]
	v_mfma_f32_16x16x32_bf16 v[56:59], v[236:239], v[68:71], v[56:59]
	v_mfma_f32_16x16x32_bf16 v[60:63], v[240:243], v[68:71], v[60:63]
	ds_read2_b64 v[228:231], v187 offset0:36 offset1:40
	ds_read2_b64 v[232:235], v188 offset0:36 offset1:40
	ds_read2_b64 v[236:239], v189 offset0:36 offset1:40
	ds_read2_b64 v[240:243], v190 offset0:36 offset1:40
	v_cvt_pk_bf16_f32 v64, v20, v21
	v_cvt_pk_bf16_f32 v65, v22, v23
	v_cvt_pk_bf16_f32 v66, v24, v25
	v_cvt_pk_bf16_f32 v67, v26, v27
	s_waitcnt lgkmcnt(0)
	s_nop 1
	v_mfma_f32_16x16x32_bf16 v[48:51], v[212:215], v[64:67], v[48:51]
	v_mfma_f32_16x16x32_bf16 v[52:55], v[216:219], v[64:67], v[52:55]
	v_mfma_f32_16x16x32_bf16 v[56:59], v[220:223], v[64:67], v[56:59]
	v_mfma_f32_16x16x32_bf16 v[60:63], v[224:227], v[64:67], v[60:63]
	ds_read_b64 v[212:213], v187 offset:352
	ds_read_b64 v[216:217], v188 offset:352
	ds_read_b64 v[220:221], v189 offset:352
	ds_read_b64 v[224:225], v190 offset:352
	v_cvt_pk_bf16_f32 v68, v28, v29
	v_cvt_pk_bf16_f32 v69, v30, v31
	v_cvt_pk_bf16_f32 v70, v32, v33
	v_cvt_pk_bf16_f32 v71, v34, v35
	s_waitcnt lgkmcnt(0)
	s_nop 1
	v_mfma_f32_16x16x32_bf16 v[48:51], v[228:231], v[68:71], v[48:51]
	v_mfma_f32_16x16x32_bf16 v[52:55], v[232:235], v[68:71], v[52:55]
	v_mfma_f32_16x16x32_bf16 v[56:59], v[236:239], v[68:71], v[56:59]
	v_mfma_f32_16x16x32_bf16 v[60:63], v[240:243], v[68:71], v[60:63]
	v_cvt_pk_bf16_f32 v64, v36, v37
	v_cvt_pk_bf16_f32 v65, v38, v39
	v_mov_b32_e32 v66, 0
	v_mov_b32_e32 v67, 0
	s_waitcnt lgkmcnt(0)
	v_mov_b32_e32 v214, 0
	v_mov_b32_e32 v215, 0
	v_mov_b32_e32 v218, 0
	v_mov_b32_e32 v219, 0
	v_mov_b32_e32 v222, 0
	v_mov_b32_e32 v223, 0
	v_mov_b32_e32 v226, 0
	v_mov_b32_e32 v227, 0
	s_nop 1
	v_mfma_f32_16x16x32_bf16 v[48:51], v[212:215], v[64:67], v[48:51]
	v_mfma_f32_16x16x32_bf16 v[52:55], v[216:219], v[64:67], v[52:55]
	v_mfma_f32_16x16x32_bf16 v[56:59], v[220:223], v[64:67], v[56:59]
	v_mfma_f32_16x16x32_bf16 v[60:63], v[224:227], v[64:67], v[60:63]
	s_nop 7
	s_nop 1
	v_pk_mul_f32 v[48:49], v[198:199], v[48:49] op_sel_hi:[0,1]
	v_pk_mul_f32 v[50:51], v[198:199], v[50:51] op_sel_hi:[0,1]
	v_pk_mul_f32 v[52:53], v[198:199], v[52:53] op_sel_hi:[0,1]
	v_pk_mul_f32 v[54:55], v[198:199], v[54:55] op_sel_hi:[0,1]
	v_pk_mul_f32 v[56:57], v[198:199], v[56:57] op_sel_hi:[0,1]
	v_pk_mul_f32 v[58:59], v[198:199], v[58:59] op_sel_hi:[0,1]
	v_pk_mul_f32 v[60:61], v[198:199], v[60:61] op_sel_hi:[0,1]
	v_pk_mul_f32 v[62:63], v[198:199], v[62:63] op_sel_hi:[0,1]
	v_pk_mul_f32 v[80:81], v[48:49], v[48:49]
	v_pk_fma_f32 v[80:81], v[50:51], v[50:51], v[80:81]
	v_pk_fma_f32 v[80:81], v[52:53], v[52:53], v[80:81]
	v_pk_fma_f32 v[80:81], v[54:55], v[54:55], v[80:81]
	v_pk_fma_f32 v[80:81], v[56:57], v[56:57], v[80:81]
	v_pk_fma_f32 v[80:81], v[58:59], v[58:59], v[80:81]
	v_pk_fma_f32 v[80:81], v[60:61], v[60:61], v[80:81]
	v_pk_fma_f32 v[80:81], v[62:63], v[62:63], v[80:81]
	v_add_f32_e32 v0, v80, v81
	ds_bpermute_b32 v1, v193, v0
	v_cvt_pk_bf16_f32 v48, v48, v49
	v_cvt_pk_bf16_f32 v49, v50, v51
	global_store_dwordx2 v191, v[48:49], s[100:101] offset:0
	v_cvt_pk_bf16_f32 v52, v52, v53
	v_cvt_pk_bf16_f32 v53, v54, v55
	global_store_dwordx2 v191, v[52:53], s[100:101] offset:32
	v_cvt_pk_bf16_f32 v56, v56, v57
	v_cvt_pk_bf16_f32 v57, v58, v59
	global_store_dwordx2 v191, v[56:57], s[100:101] offset:64
	v_cvt_pk_bf16_f32 v60, v60, v61
	v_cvt_pk_bf16_f32 v61, v62, v63
	global_store_dwordx2 v191, v[60:61], s[100:101] offset:96
	s_waitcnt lgkmcnt(0)
	v_add_f32_e32 v0, v0, v1
	ds_bpermute_b32 v1, v194, v0
	s_waitcnt lgkmcnt(0)
	v_add_f32_e32 v0, v0, v1
	s_mov_b64 exec, s[56:57]
	v_floor_f32_e32 v1, v0
	v_sub_f32_e32 v0, v0, v1
	v_mul_f32_e32 v0, 0x4f800000, v0
	v_cvt_u32_f32_e32 v47, v1
	v_cvt_u32_f32_e32 v46, v0
	global_atomic_add_x2 v192, v[46:47], s[100:101] offset:384
	s_mov_b64 exec, -1

; __global__ void __launch_bounds__(NWAVES * 64, 2) fwd_kernel(Args A) {
;     extern __shared__ __attribute__((aligned(16))) unsigned char lds[];
;     cg::grid_group grid = cg::this_grid();
	.amdhsa_kernel _Z10fwd_kernel4Args
		.amdhsa_group_segment_fixed_size 0
		.amdhsa_private_segment_fixed_size 0
		.amdhsa_kernarg_size 416
		.amdhsa_user_sgpr_count 2
		.amdhsa_user_sgpr_dispatch_ptr 0
		.amdhsa_user_sgpr_queue_ptr 0
		.amdhsa_user_sgpr_kernarg_segment_ptr 1
		.amdhsa_user_sgpr_dispatch_id 0
		.amdhsa_user_sgpr_kernarg_preload_length 0
		.amdhsa_user_sgpr_kernarg_preload_offset 0
		.amdhsa_user_sgpr_private_segment_size 0
		.amdhsa_uses_dynamic_stack 0
		.amdhsa_enable_private_segment 0
		.amdhsa_system_sgpr_workgroup_id_x 1
		.amdhsa_system_sgpr_workgroup_id_y 0
		.amdhsa_system_sgpr_workgroup_id_z 0
		.amdhsa_system_sgpr_workgroup_info 0
		.amdhsa_system_vgpr_workitem_id 2
		.amdhsa_next_free_vgpr 255
		.amdhsa_next_free_sgpr 102
		.amdhsa_accum_offset 256
		.amdhsa_reserve_vcc 1
		.amdhsa_float_round_mode_32 0
		.amdhsa_float_round_mode_16_64 0
		.amdhsa_float_denorm_mode_32 3
		.amdhsa_float_denorm_mode_16_64 3
		.amdhsa_dx10_clamp 1
		.amdhsa_ieee_mode 1
		.amdhsa_fp16_overflow 0
		.amdhsa_tg_split 0
		.amdhsa_exception_fp_ieee_invalid_op 0
		.amdhsa_exception_fp_denorm_src 0
		.amdhsa_exception_fp_ieee_div_zero 0
		.amdhsa_exception_fp_ieee_overflow 0
		.amdhsa_exception_fp_ieee_underflow 0
		.amdhsa_exception_fp_ieee_inexact 0
		.amdhsa_exception_int_div_zero 0
	.end_amdhsa_kernel

; __global__ void __launch_bounds__(NWAVES * 64, 2) fwd_kernel(Args A) {
;     extern __shared__ __attribute__((aligned(16))) unsigned char lds[];
;     cg::grid_group grid = cg::this_grid();
amdhsa.kernels:
  - .agpr_count:     0
    .args:
      - .offset:         0
        .size:           160
        .value_kind:     by_value
      - .offset:         160
        .size:           4
        .value_kind:     hidden_block_count_x
      - .offset:         164
        .size:           4
        .value_kind:     hidden_block_count_y
      - .offset:         168
        .size:           4
        .value_kind:     hidden_block_count_z
      - .offset:         172
        .size:           2
        .value_kind:     hidden_group_size_x
      - .offset:         174
        .size:           2
        .value_kind:     hidden_group_size_y
      - .offset:         176
        .size:           2
        .value_kind:     hidden_group_size_z
      - .offset:         178
        .size:           2
        .value_kind:     hidden_remainder_x
      - .offset:         180
        .size:           2
        .value_kind:     hidden_remainder_y
      - .offset:         182
        .size:           2
        .value_kind:     hidden_remainder_z
      - .offset:         200
        .size:           8
        .value_kind:     hidden_global_offset_x
      - .offset:         208
        .size:           8
        .value_kind:     hidden_global_offset_y
      - .offset:         216
        .size:           8
        .value_kind:     hidden_global_offset_z
      - .offset:         224
        .size:           2
        .value_kind:     hidden_grid_dims
      - .offset:         248
        .size:           8
        .value_kind:     hidden_multigrid_sync_arg
      - .offset:         280
        .size:           4
        .value_kind:     hidden_dynamic_lds_size
    .group_segment_fixed_size: 0
    .kernarg_segment_align: 8
    .kernarg_segment_size: 416
    .language:       OpenCL C
    .language_version:
      - 2
      - 0
    .max_flat_workgroup_size: 512
    .name:           _Z10fwd_kernel4Args
    .private_segment_fixed_size: 0
    .sgpr_count:     108
    .sgpr_spill_count: 274
    .symbol:         _Z10fwd_kernel4Args.kd
    .uniform_work_group_size: 1
    .uses_dynamic_stack: false
    .vgpr_count:     255
    .vgpr_spill_count: 0
    .wavefront_size: 64
